# DN stage b regenerated: 2 tokens x 8 dims per thread (fewer bf16 unpacks and LDS loads, packed silu scaling, DPP 8-lane norm, next-part loads prefetched); stage c2 16x16 inverse as column sweeps with
# speedup vs baseline: 1.0329x; 1.0329x over previous
; __device__ __forceinline__ u16 f2bf(float f) { return (u16)(pack2(f, 0.f) & 0xffffu); }
; __device__ __forceinline__ float bf2f(u16 h) { return __uint_as_float(((unsigned)h) << 16); }
; __device__ void dn_item(const Params& p, int l, int item, char* smem, int wv) {
;     ...
;       for (int n = 0; n < 4; ++n) {
;         const int jj = n * 16 + fr;
;         float lv[4];
; #pragma unroll
;         for (int j = 0; j < 4; ++j) {
;           int i = i0 + j;
;           float e = (i >= jj) ? __expf(gi[j] - gj[n]) : 0.f;
;           lv[j] = (i > jj) ? bi[j] * kk4[n][j] * e : 0.f;
;           Ib[i * 72 + jj] = f2bf(qk[n][j] * e);
;           rhs[n][j] = bi[j] * (bf2f(vraw[n][j]) - eg[j] * rhs[n][j]);
;         }
;         *(float4*)(LfT + jj * 68 + i0) = make_float4(lv[0], lv[1], lv[2], lv[3]);
;       }
;     }
;     lds_barrier();
; #pragma unroll
;     for (int n = 0; n < 4; ++n)
; #pragma unroll
;       for (int j = 0; j < 4; ++j) X[(16 * wave + fq * 4 + j) * XS + n * 16 + fr] = rhs[n][j];
;     {
;       const int c = lane & 15;
;       const float* ld = LfT + (16 * wave) * 68 + 16 * wave;
;       float x[16];
; #pragma unroll
;       for (int i = 0; i < 16; ++i) x[i] = (i == c) ? 1.f : 0.f;
.LBB0_334:
	s_movk_i32 s14, 0xc0
	s_or_b64 exec, exec, s[2:3]
	v_ashrrev_i32_e32 v41, 2, v78
	v_readlane_b32 s6, v253, 40
	v_sub_u32_e32 v0, 63, v41
	v_readlane_b32 s7, v253, 41
	v_ashrrev_i32_e32 v38, 6, v78
	v_lshrrev_b32_e32 v39, 4, v31
	v_cndmask_b32_e64 v42, v0, v41, s[6:7]
	v_lshlrev_b32_e32 v0, 4, v78
	v_and_b32_e32 v40, 15, v78
	v_and_b32_e32 v43, 48, v0
	v_lshlrev_b32_e32 v0, 2, v39
	v_readlane_b32 s3, v254, 2
	v_lshlrev_b32_e32 v48, 4, v38
	v_or_b32_e32 v49, v0, v48
	v_add_u32_e32 v47, s3, v0
	v_or_b32_e32 v0, v48, v40
	v_and_b32_e32 v48, 48, v31
	s_add_i32 s0, 16, 0x13040
	v_add_u32_e32 v80, 16, v48
	s_movk_i32 s4, 0x90
	v_lshl_add_u32 v186, v43, 2, s0
	s_waitcnt vmcnt(0)
	v_mad_u64_u32 v[82:83], s[0:1], v0, s4, v[80:81]
	s_movk_i32 s0, 0x1100
	v_and_b32_e32 v0, 48, v78
	v_mul_lo_u32 v51, v38, s0
	v_readlane_b32 s0, v253, 58
	v_add_u32_e32 v83, 16, v0
	v_lshlrev_b32_e32 v0, 1, v40
	v_readlane_b32 s1, v253, 59
	v_lshl_add_u32 v32, v43, 1, 16
	v_lshlrev_b32_e32 v46, 2, v40
	v_lshl_add_u64 v[84:85], s[0:1], 0, v[0:1]
	v_cmp_eq_u32_e64 s[0:1], 0, v31
	v_and_b32_e32 v52, 0xffffffc0, v78
	v_lshlrev_b32_e32 v44, 2, v31
	v_writelane_b32 v254, s0, 38
	v_add_u32_e32 v189, 16, v46
	v_add3_u32 v191, 16, v51, v52
	v_writelane_b32 v254, s1, 39
	v_cmp_gt_u32_e64 s[0:1], 2, v31
	v_and_b32_e32 v51, -16, v41
	v_add_u32_e32 v193, v189, v52
	v_writelane_b32 v254, s0, 40
	v_add_u32_e32 v52, 16, v44
	v_mul_u32_u24_e32 v53, 0x8c, v31
	v_writelane_b32 v254, s1, 41
	v_cndmask_b32_e64 v196, v33, v30, s[0:1]
	v_cmp_gt_u32_e64 s[0:1], 4, v31
	v_lshlrev_b32_e32 v54, 1, v51
	v_cmp_ne_u32_e32 vcc, 0, v31
	v_writelane_b32 v254, s0, 42
	v_cmp_gt_u32_e64 s[46:47], 16, v31
	v_add3_u32 v194, v52, v53, v54
	v_writelane_b32 v254, s1, 43
	v_cndmask_b32_e64 v197, v34, v30, s[0:1]
	v_cmp_gt_u32_e64 s[0:1], 8, v31
	v_mov_b32_e32 v34, 0x1b00
	v_mad_u32_u24 v204, v40, s4, v34
	v_writelane_b32 v254, s0, 44
	v_or_b32_e32 v34, 1, v49
	v_subbrev_co_u32_e32 v53, vcc, 0, v78, vcc
	v_writelane_b32 v254, s1, 45
	v_cndmask_b32_e64 v198, v35, v30, s[0:1]
	v_cmp_gt_u32_e64 s[0:1], 32, v31
	v_or_b32_e32 v35, 3, v49
	v_cndmask_b32_e64 v199, v36, v30, s[46:47]
	v_writelane_b32 v254, s0, 46
	v_or_b32_e32 v36, 2, v49
	v_cmp_eq_u32_e32 vcc, 0, v40
	v_writelane_b32 v254, s1, 47
	v_cndmask_b32_e64 v200, v37, v30, s[0:1]
	s_movk_i32 s0, 0x190
	v_mad_u64_u32 v[86:87], s[0:1], v41, s0, v[32:33]
	v_mad_u64_u32 v[88:89], s[0:1], v42, s4, v[32:33]
	v_cmp_gt_i32_e64 s[0:1], v49, v40
	v_cndmask_b32_e64 v218, 0, 1.0, vcc
	v_cmp_eq_u32_e32 vcc, 1, v40
	v_writelane_b32 v254, s0, 48
	v_or_b32_e32 v31, 16, v40
	v_cndmask_b32_e64 v219, 0, 1.0, vcc
	v_writelane_b32 v254, s1, 49
	v_cmp_lt_i32_e64 s[0:1], v34, v40
	v_cmp_eq_u32_e32 vcc, 2, v40
	v_lshlrev_b32_e32 v38, 10, v38
	v_writelane_b32 v254, s0, 50
	v_cndmask_b32_e64 v220, 0, 1.0, vcc
	v_cmp_eq_u32_e32 vcc, 3, v40
	v_writelane_b32 v254, s1, 51
	v_cmp_lt_i32_e64 s[0:1], v35, v40
	v_cndmask_b32_e64 v221, 0, 1.0, vcc
	v_cmp_eq_u32_e32 vcc, 4, v40
	v_writelane_b32 v254, s0, 52
	v_mov_b32_e32 v32, 0x900
	v_cndmask_b32_e64 v222, 0, 1.0, vcc
	v_writelane_b32 v254, s1, 53
	v_cmp_lt_i32_e64 s[0:1], v36, v40
	v_cmp_eq_u32_e32 vcc, 5, v40
	v_mov_b32_e32 v33, 0x1200
	v_writelane_b32 v254, s0, 54
	v_cndmask_b32_e64 v223, 0, 1.0, vcc
	v_cmp_eq_u32_e32 vcc, 6, v40
	v_writelane_b32 v254, s1, 55
	v_cmp_gt_i32_e64 s[0:1], v35, v40
	v_cndmask_b32_e64 v224, 0, 1.0, vcc
	v_cmp_eq_u32_e32 vcc, 7, v40
	v_writelane_b32 v254, s0, 56
	v_sub_u32_e32 v190, v189, v0
	v_cndmask_b32_e64 v225, 0, 1.0, vcc
	v_writelane_b32 v254, s1, 57
	v_cmp_gt_i32_e64 s[0:1], v36, v40
	v_cmp_eq_u32_e32 vcc, 8, v40
	v_add3_u32 v192, s3, v38, v46
	v_writelane_b32 v254, s0, 58
	v_cndmask_b32_e64 v226, 0, 1.0, vcc
	v_cmp_eq_u32_e32 vcc, 9, v40
	v_writelane_b32 v254, s1, 59
	v_cmp_gt_i32_e64 s[0:1], v49, v31
	v_cndmask_b32_e64 v227, 0, 1.0, vcc
	v_cmp_eq_u32_e32 vcc, 10, v40
	v_writelane_b32 v254, s0, 60
	v_lshlrev_b32_e32 v38, 6, v40
	v_cndmask_b32_e64 v228, 0, 1.0, vcc
	v_writelane_b32 v254, s1, 61
	v_cmp_lt_i32_e64 s[0:1], v34, v31
	v_cmp_eq_u32_e32 vcc, 11, v40
	v_mul_u32_u24_e32 v87, 0x90, v40
	v_writelane_b32 v254, s0, 62
	v_cndmask_b32_e64 v229, 0, 1.0, vcc
	v_cmp_eq_u32_e32 vcc, 12, v40
	v_writelane_b32 v254, s1, 63
	v_cmp_lt_i32_e64 s[0:1], v35, v31
; __device__ void dn_item(const Params& p, int l, int item, char* smem, int wv) {
;     ...
;       const int ti = tid >> 2, dc = tid & 3;
;       const int ip = dir ? 63 - ti : ti;
;       const float ekd = __expf(gcs[63] - gcs[ip]);
; #pragma unroll
;       for (int part = 0; part < 3; ++part) {
;         float acc[16];
; #pragma unroll
;         for (int e = 0; e < 16; ++e) acc[e] = 0.f;
; #pragma unroll
;         for (int kb2 = 0; kb2 < 2; ++kb2) {
;           const int k0 = kb2 * 3, nk = kb2 ? 2 : 3;
;           uint4 rv[3][2];
;           float4 wv4[3][4];
; #pragma unroll
;           for (int kq = 0; kq < 3; ++kq) {
;             if (kq < nk) {
;               const int kk = k0 + kq;
;               const u16* rr = R0 + (ti + kk) * RS + part * 64 + dc * 16;
;               rv[kq][0] = *(const uint4*)rr;
;               rv[kq][1] = *(const uint4*)(rr + 8);
;               const float* wp = cw + kk * 192 + part * 64 + dc * 16;
; #pragma unroll
;               for (int e4 = 0; e4 < 4; ++e4) wv4[kq][e4] = *(const float4*)(wp + e4 * 4);
;             }
;           }
;           __builtin_amdgcn_sched_barrier(0);
; #pragma unroll
;           for (int kq = 0; kq < 3; ++kq) {
;             if (kq < nk) {
;               unsigned rw[8] = {rv[kq][0].x, rv[kq][0].y, rv[kq][0].z, rv[kq][0].w, rv[kq][1].x, rv[kq][1].y, rv[kq][1].z, rv[kq][1].w};
; #pragma unroll
;               for (int e4 = 0; e4 < 4; ++e4) {
;                 float4 w = wv4[kq][e4];
;                 acc[e4 * 4 + 0] += w.x * __uint_as_float(rw[e4 * 2] << 16);
;                 acc[e4 * 4 + 1] += w.y * __uint_as_float(rw[e4 * 2] & 0xffff0000u);
;                 acc[e4 * 4 + 2] += w.z * __uint_as_float(rw[e4 * 2 + 1] << 16);
;                 acc[e4 * 4 + 3] += w.w * __uint_as_float(rw[e4 * 2 + 1] & 0xffff0000u);
;               }
;             }
;           }
;           __builtin_amdgcn_sched_barrier(0);
;         }
;         float ss = 0.f;
; #pragma unroll
;         for (int e = 0; e < 16; ++e) { acc[e] = siluf_(acc[e]); ss += acc[e] * acc[e]; }
;         float sc = 1.f;
;         if (part < 2) {
;           ss += shx(ss, 1, lane);
;           ss += shx(ss, 2, lane);
;           sc = rsqrtf(ss + 1e-6f) * (part == 0 ? 0.125f : 1.f);
;         }
; #pragma unroll
;         for (int e = 0; e < 16; ++e) acc[e] *= sc;
;         u16* dst = (part == 0 ? Qb : (part == 1 ? Kb : Vb)) + ip * 72 + dc * 16;
	v_cndmask_b32_e64 v230, 0, 1.0, vcc
	v_cmp_eq_u32_e32 vcc, 13, v40
	v_writelane_b32 v255, s0, 0
	v_mad_u32_u24 v89, v40, s4, v32
	v_cndmask_b32_e64 v231, 0, 1.0, vcc
	v_writelane_b32 v255, s1, 1
	v_cmp_lt_i32_e64 s[0:1], v36, v31
	v_cmp_eq_u32_e32 vcc, 14, v40
	v_or_b32_e32 v32, 32, v40
	v_writelane_b32 v255, s0, 2
	v_mad_u32_u24 v203, v40, s4, v33
	v_or_b32_e32 v33, 48, v40
	v_writelane_b32 v255, s1, 3
	v_cmp_gt_i32_e64 s[0:1], v35, v31
	v_add_u32_e32 v217, 16, v0
	v_cmp_lt_i32_e64 s[50:51], v49, v40
	v_mul_u32_u24_e32 v0, 0x110, v40
	v_writelane_b32 v255, s0, 4
	v_cndmask_b32_e64 v232, 0, 1.0, vcc
	v_cmp_eq_u32_e32 vcc, 15, v40
	v_or_b32_e32 v40, 15, v41
	v_sub_u32_e32 v41, 63, v49
	v_writelane_b32 v255, s1, 5
	v_cmp_gt_i32_e64 s[0:1], v36, v31
	v_cndmask_b32_e64 v235, v41, v49, s[6:7]
	v_sub_u32_e32 v41, 63, v34
	s_add_i32 s2, 16, 0x11e40
	v_lshlrev_b32_e32 v48, 2, v49
	s_add_i32 s3, 16, 0x11f40
	v_lshlrev_b32_e32 v37, 2, v36
	v_writelane_b32 v255, s0, 6
	v_cmp_lt_i32_e64 s[82:83], v34, v32
	v_cmp_lt_i32_e64 s[96:97], v34, v33
	s_movk_i32 s15, 0x110
	v_cndmask_b32_e64 v236, v41, v34, s[6:7]
	v_sub_u32_e32 v34, 63, v36
	v_lshl_add_u32 v185, v42, 2, s2
	v_lshl_add_u32 v45, v42, 1, 16
	v_add_u32_e32 v50, 16, v48
	v_add_u32_e32 v201, s2, v44
	v_add_u32_e32 v202, s3, v44
	v_mul_u32_u24_e32 v30, 0x90, v43
	v_add_u32_e32 v205, s2, v48
	v_add_u32_e32 v206, s3, v48
	v_add_u32_e32 v207, s2, v46
	v_lshl_add_u32 v208, v31, 2, s2
	v_lshl_add_u32 v209, v32, 2, s2
	v_add_u32_e32 v210, s2, v37
	v_add_u32_e32 v211, s3, v37
	v_lshl_add_u32 v212, v35, 2, s2
	v_lshl_add_u32 v213, v33, 2, s2
	v_mul_lo_u32 v214, v49, s4
	v_mul_lo_u32 v215, v36, s4
	v_mul_lo_u32 v216, v35, s4
	v_cmp_lt_i32_e64 s[64:65], v49, v31
	v_writelane_b32 v255, s1, 7
	v_cmp_lt_i32_e64 s[78:79], v49, v32
	v_cmp_gt_i32_e64 s[80:81], v49, v32
	v_cmp_lt_i32_e64 s[84:85], v35, v32
	v_cmp_lt_i32_e64 s[86:87], v36, v32
	v_cmp_gt_i32_e64 s[88:89], v35, v32
	v_cmp_gt_i32_e64 s[90:91], v36, v32
	v_cmp_lt_i32_e64 s[92:93], v49, v33
	v_cmp_gt_i32_e64 s[48:49], v49, v33
	v_cmp_lt_i32_e64 s[98:99], v35, v33
	v_cmp_lt_i32_e64 s[0:1], v36, v33
	v_cmp_gt_i32_e64 s[2:3], v35, v33
	v_cmp_gt_i32_e64 s[4:5], v36, v33
	v_mul_lo_u32 v31, v49, s15
	v_mul_lo_u32 v32, v36, s15
	v_mul_lo_u32 v33, v35, s15
	v_mul_u32_u24_e32 v234, 0x110, v39
	v_mul_u32_u24_e32 v37, 0x440, v39
	v_mul_lo_u32 v39, v51, s15
	v_mul_lo_u32 v40, v40, s15
	v_cndmask_b32_e64 v237, v34, v36, s[6:7]
	v_sub_u32_e32 v34, 63, v35
	v_mov_b32_e32 v90, 0
	v_xor_b32_e32 v187, 4, v44
	v_xor_b32_e32 v188, 8, v44
	v_lshlrev_b32_e32 v195, 2, v53
	v_cndmask_b32_e64 v233, 0, 1.0, vcc
	v_cndmask_b32_e64 v238, v34, v35, s[6:7]
	s_mov_b32 s42, -4
	v_add_u32_e32 v239, v45, v30
	v_add_u32_e32 v240, v50, v0
	v_add_u32_e32 v241, v189, v31
	v_add_u32_e32 v242, v189, v32
	v_add_u32_e32 v243, v189, v33
	v_add_u32_e32 v244, v47, v38
	v_add_u32_e32 v245, v193, v37
	v_add_u32_e32 v246, v52, v39
	v_add_u32_e32 v247, v52, v40
	v_mov_b32_e32 v91, v90
	v_mov_b32_e32 v92, v90
	v_mov_b32_e32 v93, v90
	v_mov_b32_e32 v94, v90
	v_mov_b32_e32 v95, v90
	v_mov_b32_e32 v96, v90
	v_mov_b32_e32 v97, v90
	v_mov_b32_e32 v98, v90
	v_mov_b32_e32 v99, v90
	v_mov_b32_e32 v100, v90
	v_mov_b32_e32 v101, v90
	v_mov_b32_e32 v102, v90
	v_mov_b32_e32 v103, v90
	v_mov_b32_e32 v104, v90
	v_mov_b32_e32 v105, v90
	v_lshrrev_b32_e32 v30, 3, v78
	v_and_b32_e32 v31, 7, v78
	v_lshlrev_b32_e32 v32, 4, v31
	v_mul_u32_u24_e32 v187, 0x320, v30
	v_add3_u32 v187, v187, v32, 16
	v_lshlrev_b32_e32 v188, 5, v31
	v_add_u32_e32 v188, 0x13050, v188
	v_lshlrev_b32_e32 v33, 1, v30
	v_sub_u32_e32 v34, 63, v33
	v_readlane_b32 s6, v253, 40
	v_readlane_b32 s7, v253, 41
	v_add_u32_e32 v35, 1, v33
	v_add_u32_e32 v36, -1, v34
	v_cndmask_b32_e64 v33, v34, v33, s[6:7]
	v_cndmask_b32_e64 v35, v36, v35, s[6:7]
	v_cndmask_b32_e64 v36, v35, v33, s[6:7]
	v_mul_u32_u24_e32 v195, 0x90, v33
	v_mul_u32_u24_e32 v196, 0x90, v35
	v_add3_u32 v195, v195, v32, 16
	v_add3_u32 v196, v196, v32, 16
	v_mul_u32_u24_e32 v197, 0x480, v31
	v_lshl_add_u32 v197, v36, 1, v197
	v_add_u32_e32 v197, 0xd650, v197
	v_lshlrev_b32_e32 v198, 2, v33
	v_lshlrev_b32_e32 v199, 2, v35
	v_add_u32_e32 v198, 0x11e50, v198
	v_add_u32_e32 v199, 0x11e50, v199
	s_waitcnt lgkmcnt(0)
	s_barrier
	s_branch .LBB0_339

; __device__ void dn_item(const Params& p, int l, int item, char* smem, int wv) {
;     ...
;       const float ekd = __expf(gcs[63] - gcs[ip]);
; #pragma unroll
;       for (int part = 0; part < 3; ++part) {
;         float acc[16];
; #pragma unroll
;         for (int e = 0; e < 16; ++e) acc[e] = 0.f;
; #pragma unroll
;         for (int kb2 = 0; kb2 < 2; ++kb2) {
;           const int k0 = kb2 * 3, nk = kb2 ? 2 : 3;
;           uint4 rv[3][2];
;           float4 wv4[3][4];
; #pragma unroll
;           for (int kq = 0; kq < 3; ++kq) {
;             if (kq < nk) {
;               const int kk = k0 + kq;
;               const u16* rr = R0 + (ti + kk) * RS + part * 64 + dc * 16;
;               rv[kq][0] = *(const uint4*)rr;
;               rv[kq][1] = *(const uint4*)(rr + 8);
;               const float* wp = cw + kk * 192 + part * 64 + dc * 16;
; #pragma unroll
;               for (int e4 = 0; e4 < 4; ++e4) wv4[kq][e4] = *(const float4*)(wp + e4 * 4);
;             }
;           }
;           __builtin_amdgcn_sched_barrier(0);
; #pragma unroll
;           for (int kq = 0; kq < 3; ++kq) {
;             if (kq < nk) {
;               unsigned rw[8] = {rv[kq][0].x, rv[kq][0].y, rv[kq][0].z, rv[kq][0].w, rv[kq][1].x, rv[kq][1].y, rv[kq][1].z, rv[kq][1].w};
; #pragma unroll
;               for (int e4 = 0; e4 < 4; ++e4) {
;                 float4 w = wv4[kq][e4];
;                 acc[e4 * 4 + 0] += w.x * __uint_as_float(rw[e4 * 2] << 16);
;                 acc[e4 * 4 + 1] += w.y * __uint_as_float(rw[e4 * 2] & 0xffff0000u);
;                 acc[e4 * 4 + 2] += w.z * __uint_as_float(rw[e4 * 2 + 1] << 16);
;                 acc[e4 * 4 + 3] += w.w * __uint_as_float(rw[e4 * 2 + 1] & 0xffff0000u);
;               }
;             }
;           }
;           __builtin_amdgcn_sched_barrier(0);
.LBB0_339:
	v_add_co_u32_e64 v0, s[44:45], s42, 4
	v_readlane_b32 s6, v254, 3
	v_readfirstlane_b32 s43, v0
	s_nop 0
	v_mov_b32_e32 v0, s6
	ds_read_b32 v132, v0
	ds_read_b32 v133, v198
	ds_read_b32 v134, v199
	ds_read_b128 v[30:33], v187 offset:0
	ds_read_b128 v[34:37], v187 offset:400
	ds_read_b128 v[38:41], v187 offset:800
	ds_read_b128 v[42:45], v187 offset:1200
	ds_read_b128 v[46:49], v187 offset:1600
	ds_read_b128 v[50:53], v187 offset:2000
	ds_read_b128 v[54:57], v188 offset:0
	ds_read_b128 v[58:61], v188 offset:16
	ds_read_b128 v[62:65], v188 offset:768
	ds_read_b128 v[66:69], v188 offset:784
	ds_read_b128 v[70:73], v188 offset:1536
	ds_read_b128 v[74:77], v188 offset:1552
	ds_read_b128 v[106:109], v188 offset:2304
	ds_read_b128 v[110:113], v188 offset:2320
	ds_read_b128 v[114:117], v188 offset:3072
	ds_read_b128 v[118:121], v188 offset:3088
	s_mov_b32 s15, 0x800000
	v_mov_b32_e32 v176, 0xbfb8aa3b
	v_mov_b32_e32 v180, 1.0
	s_waitcnt lgkmcnt(10)
	v_lshlrev_b32_e32 v122, 16, v30
	v_and_b32_e32 v123, 0xffff0000, v30
	v_lshlrev_b32_e32 v160, 16, v31
	v_and_b32_e32 v161, 0xffff0000, v31
	v_lshlrev_b32_e32 v124, 16, v34
	v_and_b32_e32 v125, 0xffff0000, v34
	v_lshlrev_b32_e32 v162, 16, v35
	v_and_b32_e32 v163, 0xffff0000, v35
	v_lshlrev_b32_e32 v126, 16, v38
	v_and_b32_e32 v127, 0xffff0000, v38
	v_lshlrev_b32_e32 v164, 16, v39
	v_and_b32_e32 v165, 0xffff0000, v39
	v_lshlrev_b32_e32 v128, 16, v42
	v_and_b32_e32 v129, 0xffff0000, v42
	v_lshlrev_b32_e32 v166, 16, v43
	v_and_b32_e32 v167, 0xffff0000, v43
	v_lshlrev_b32_e32 v140, 16, v46
	v_and_b32_e32 v141, 0xffff0000, v46
	v_lshlrev_b32_e32 v168, 16, v47
	v_and_b32_e32 v169, 0xffff0000, v47
	v_lshlrev_b32_e32 v142, 16, v50
	v_and_b32_e32 v143, 0xffff0000, v50
	v_lshlrev_b32_e32 v170, 16, v51
	v_and_b32_e32 v171, 0xffff0000, v51
	v_sub_f32_e32 v133, v132, v133
	v_sub_f32_e32 v134, v132, v134
	v_mul_f32_e32 v133, 0x3fb8aa3b, v133
	v_mul_f32_e32 v134, 0x3fb8aa3b, v134
	v_exp_f32_e32 v133, v133
	v_exp_f32_e32 v134, v134
	s_waitcnt lgkmcnt(8)
	v_pk_fma_f32 v[144:145], v[54:55], v[122:123], 0 op_sel_hi:[1,1,0]
	v_pk_fma_f32 v[152:153], v[54:55], v[124:125], 0 op_sel_hi:[1,1,0]
	v_pk_fma_f32 v[146:147], v[56:57], v[160:161], 0 op_sel_hi:[1,1,0]
	v_pk_fma_f32 v[154:155], v[56:57], v[162:163], 0 op_sel_hi:[1,1,0]
	s_waitcnt lgkmcnt(6)
	v_pk_fma_f32 v[144:145], v[62:63], v[124:125], v[144:145]
	v_pk_fma_f32 v[152:153], v[62:63], v[126:127], v[152:153]
	v_pk_fma_f32 v[146:147], v[64:65], v[162:163], v[146:147]
	v_pk_fma_f32 v[154:155], v[64:65], v[164:165], v[154:155]
	s_waitcnt lgkmcnt(4)
	v_pk_fma_f32 v[144:145], v[70:71], v[126:127], v[144:145]
	v_pk_fma_f32 v[152:153], v[70:71], v[128:129], v[152:153]
	v_pk_fma_f32 v[146:147], v[72:73], v[164:165], v[146:147]
	v_pk_fma_f32 v[154:155], v[72:73], v[166:167], v[154:155]
	s_waitcnt lgkmcnt(2)
	v_pk_fma_f32 v[144:145], v[106:107], v[128:129], v[144:145]
	v_pk_fma_f32 v[152:153], v[106:107], v[140:141], v[152:153]
	v_pk_fma_f32 v[146:147], v[108:109], v[166:167], v[146:147]
	v_pk_fma_f32 v[154:155], v[108:109], v[168:169], v[154:155]
	s_waitcnt lgkmcnt(0)
	v_pk_fma_f32 v[144:145], v[114:115], v[140:141], v[144:145]
	v_pk_fma_f32 v[152:153], v[114:115], v[142:143], v[152:153]
	v_pk_fma_f32 v[146:147], v[116:117], v[168:169], v[146:147]
	v_pk_fma_f32 v[154:155], v[116:117], v[170:171], v[154:155]
	v_lshlrev_b32_e32 v122, 16, v32
	v_and_b32_e32 v123, 0xffff0000, v32
	v_lshlrev_b32_e32 v160, 16, v33
	v_and_b32_e32 v161, 0xffff0000, v33
	v_lshlrev_b32_e32 v124, 16, v36
	v_and_b32_e32 v125, 0xffff0000, v36
	v_lshlrev_b32_e32 v162, 16, v37
	v_and_b32_e32 v163, 0xffff0000, v37
	v_lshlrev_b32_e32 v126, 16, v40
	v_and_b32_e32 v127, 0xffff0000, v40
	v_lshlrev_b32_e32 v164, 16, v41
	v_and_b32_e32 v165, 0xffff0000, v41
	v_lshlrev_b32_e32 v128, 16, v44
	v_and_b32_e32 v129, 0xffff0000, v44
	v_lshlrev_b32_e32 v166, 16, v45
	v_and_b32_e32 v167, 0xffff0000, v45
	v_lshlrev_b32_e32 v140, 16, v48
	v_and_b32_e32 v141, 0xffff0000, v48
	v_lshlrev_b32_e32 v168, 16, v49
	v_and_b32_e32 v169, 0xffff0000, v49
	v_lshlrev_b32_e32 v142, 16, v52
	v_and_b32_e32 v143, 0xffff0000, v52
	v_lshlrev_b32_e32 v170, 16, v53
	v_and_b32_e32 v171, 0xffff0000, v53
	v_pk_fma_f32 v[148:149], v[58:59], v[122:123], 0 op_sel_hi:[1,1,0]
	v_pk_fma_f32 v[156:157], v[58:59], v[124:125], 0 op_sel_hi:[1,1,0]
	v_pk_fma_f32 v[150:151], v[60:61], v[160:161], 0 op_sel_hi:[1,1,0]
	v_pk_fma_f32 v[158:159], v[60:61], v[162:163], 0 op_sel_hi:[1,1,0]
	v_pk_fma_f32 v[148:149], v[66:67], v[124:125], v[148:149]
	v_pk_fma_f32 v[156:157], v[66:67], v[126:127], v[156:157]
	v_pk_fma_f32 v[150:151], v[68:69], v[162:163], v[150:151]
	v_pk_fma_f32 v[158:159], v[68:69], v[164:165], v[158:159]
	v_pk_fma_f32 v[148:149], v[74:75], v[126:127], v[148:149]
	v_pk_fma_f32 v[156:157], v[74:75], v[128:129], v[156:157]
	v_pk_fma_f32 v[150:151], v[76:77], v[164:165], v[150:151]
	v_pk_fma_f32 v[158:159], v[76:77], v[166:167], v[158:159]
	v_pk_fma_f32 v[148:149], v[110:111], v[128:129], v[148:149]
	v_pk_fma_f32 v[156:157], v[110:111], v[140:141], v[156:157]
	v_pk_fma_f32 v[150:151], v[112:113], v[166:167], v[150:151]
	v_pk_fma_f32 v[158:159], v[112:113], v[168:169], v[158:159]
	v_pk_fma_f32 v[148:149], v[118:119], v[140:141], v[148:149]
	v_pk_fma_f32 v[156:157], v[118:119], v[142:143], v[156:157]
	v_pk_fma_f32 v[150:151], v[120:121], v[168:169], v[150:151]
	v_pk_fma_f32 v[158:159], v[120:121], v[170:171], v[158:159]
	ds_read_b128 v[30:33], v187 offset:128
	ds_read_b128 v[34:37], v187 offset:528
	ds_read_b128 v[38:41], v187 offset:928
	ds_read_b128 v[42:45], v187 offset:1328
	ds_read_b128 v[46:49], v187 offset:1728
	ds_read_b128 v[50:53], v187 offset:2128
; __device__ __forceinline__ float siluf_(float x) { return x * __builtin_amdgcn_rcpf(1.f + __expf(-x)); }
; __device__ void dn_item(const Params& p, int l, int item, char* smem, int wv) {
;     ...
;         float ss = 0.f;
; #pragma unroll
;         for (int e = 0; e < 16; ++e) { acc[e] = siluf_(acc[e]); ss += acc[e] * acc[e]; }
;         float sc = 1.f;
;         if (part < 2) {
;           ss += shx(ss, 1, lane);
;           ss += shx(ss, 2, lane);
;           sc = rsqrtf(ss + 1e-6f) * (part == 0 ? 0.125f : 1.f);
;         }
; #pragma unroll
;         for (int e = 0; e < 16; ++e) acc[e] *= sc;
;         u16* dst = (part == 0 ? Qb : (part == 1 ? Kb : Vb)) + ip * 72 + dc * 16;
;         *(uint4*)dst = make_uint4(pack2(acc[0], acc[1]), pack2(acc[2], acc[3]), pack2(acc[4], acc[5]), pack2(acc[6], acc[7]));
;         *(uint4*)(dst + 8) = make_uint4(pack2(acc[8], acc[9]), pack2(acc[10], acc[11]), pack2(acc[12], acc[13]), pack2(acc[14], acc[15]));
	ds_read_b128 v[54:57], v188 offset:256
	ds_read_b128 v[58:61], v188 offset:272
	ds_read_b128 v[62:65], v188 offset:1024
	ds_read_b128 v[66:69], v188 offset:1040
	ds_read_b128 v[70:73], v188 offset:1792
	ds_read_b128 v[74:77], v188 offset:1808
	ds_read_b128 v[106:109], v188 offset:2560
	ds_read_b128 v[110:113], v188 offset:2576
	ds_read_b128 v[114:117], v188 offset:3328
	ds_read_b128 v[118:121], v188 offset:3344
	v_pk_mul_f32 v[160:161], v[144:145], v[176:177] op_sel_hi:[1,0]
	v_pk_mul_f32 v[162:163], v[146:147], v[176:177] op_sel_hi:[1,0]
	v_pk_mul_f32 v[164:165], v[148:149], v[176:177] op_sel_hi:[1,0]
	v_pk_mul_f32 v[166:167], v[150:151], v[176:177] op_sel_hi:[1,0]
	v_pk_mul_f32 v[168:169], v[152:153], v[176:177] op_sel_hi:[1,0]
	v_pk_mul_f32 v[170:171], v[154:155], v[176:177] op_sel_hi:[1,0]
	v_pk_mul_f32 v[172:173], v[156:157], v[176:177] op_sel_hi:[1,0]
	v_pk_mul_f32 v[174:175], v[158:159], v[176:177] op_sel_hi:[1,0]
	v_exp_f32_e32 v160, v160
	v_exp_f32_e32 v161, v161
	v_exp_f32_e32 v162, v162
	v_exp_f32_e32 v163, v163
	v_exp_f32_e32 v164, v164
	v_exp_f32_e32 v165, v165
	v_exp_f32_e32 v166, v166
	v_exp_f32_e32 v167, v167
	v_exp_f32_e32 v168, v168
	v_exp_f32_e32 v169, v169
	v_exp_f32_e32 v170, v170
	v_exp_f32_e32 v171, v171
	v_exp_f32_e32 v172, v172
	v_exp_f32_e32 v173, v173
	v_exp_f32_e32 v174, v174
	v_exp_f32_e32 v175, v175
	v_pk_add_f32 v[160:161], v[160:161], v[180:181] op_sel_hi:[1,0]
	v_pk_add_f32 v[162:163], v[162:163], v[180:181] op_sel_hi:[1,0]
	v_pk_add_f32 v[164:165], v[164:165], v[180:181] op_sel_hi:[1,0]
	v_pk_add_f32 v[166:167], v[166:167], v[180:181] op_sel_hi:[1,0]
	v_pk_add_f32 v[168:169], v[168:169], v[180:181] op_sel_hi:[1,0]
	v_pk_add_f32 v[170:171], v[170:171], v[180:181] op_sel_hi:[1,0]
	v_pk_add_f32 v[172:173], v[172:173], v[180:181] op_sel_hi:[1,0]
	v_pk_add_f32 v[174:175], v[174:175], v[180:181] op_sel_hi:[1,0]
	v_rcp_f32_e32 v160, v160
	v_rcp_f32_e32 v161, v161
	v_rcp_f32_e32 v162, v162
	v_rcp_f32_e32 v163, v163
	v_rcp_f32_e32 v164, v164
	v_rcp_f32_e32 v165, v165
	v_rcp_f32_e32 v166, v166
	v_rcp_f32_e32 v167, v167
	v_rcp_f32_e32 v168, v168
	v_rcp_f32_e32 v169, v169
	v_rcp_f32_e32 v170, v170
	v_rcp_f32_e32 v171, v171
	v_rcp_f32_e32 v172, v172
	v_rcp_f32_e32 v173, v173
	v_rcp_f32_e32 v174, v174
	v_rcp_f32_e32 v175, v175
	s_nop 0
	v_pk_mul_f32 v[144:145], v[144:145], v[160:161]
	v_pk_mul_f32 v[146:147], v[146:147], v[162:163]
	v_pk_mul_f32 v[148:149], v[148:149], v[164:165]
	v_pk_mul_f32 v[150:151], v[150:151], v[166:167]
	v_pk_mul_f32 v[152:153], v[152:153], v[168:169]
	v_pk_mul_f32 v[154:155], v[154:155], v[170:171]
	v_pk_mul_f32 v[156:157], v[156:157], v[172:173]
	v_pk_mul_f32 v[158:159], v[158:159], v[174:175]
	v_pk_mul_f32 v[160:161], v[144:145], v[144:145]
	v_pk_mul_f32 v[162:163], v[146:147], v[146:147]
	v_pk_mul_f32 v[164:165], v[148:149], v[148:149]
	v_pk_mul_f32 v[166:167], v[150:151], v[150:151]
	v_pk_mul_f32 v[168:169], v[152:153], v[152:153]
	v_pk_mul_f32 v[170:171], v[154:155], v[154:155]
	v_pk_mul_f32 v[172:173], v[156:157], v[156:157]
	v_pk_mul_f32 v[174:175], v[158:159], v[158:159]
	v_pk_add_f32 v[160:161], v[160:161], v[162:163]
	v_pk_add_f32 v[164:165], v[164:165], v[166:167]
	v_pk_add_f32 v[168:169], v[168:169], v[170:171]
	v_pk_add_f32 v[172:173], v[172:173], v[174:175]
	v_pk_add_f32 v[160:161], v[160:161], v[164:165]
	v_pk_add_f32 v[168:169], v[168:169], v[172:173]
	v_add_f32_e32 v136, v160, v161
	v_add_f32_e32 v138, v168, v169
	s_nop 1
	v_add_f32_dpp v135, v136, v136 quad_perm:[1,0,3,2] row_mask:0xf bank_mask:0xf
	v_add_f32_dpp v137, v138, v138 quad_perm:[1,0,3,2] row_mask:0xf bank_mask:0xf
	s_nop 1
	v_add_f32_dpp v136, v135, v135 quad_perm:[2,3,0,1] row_mask:0xf bank_mask:0xf
	v_add_f32_dpp v138, v137, v137 quad_perm:[2,3,0,1] row_mask:0xf bank_mask:0xf
	s_nop 1
	v_add_f32_dpp v135, v136, v136 row_half_mirror row_mask:0xf bank_mask:0xf
	v_add_f32_dpp v137, v138, v138 row_half_mirror row_mask:0xf bank_mask:0xf
	v_add_f32_e32 v136, 0x358637bd, v135
	v_cmp_gt_f32_e32 vcc, s15, v136
	v_mul_f32_e32 v139, 0x4b800000, v136
	s_nop 0
	v_cndmask_b32_e32 v136, v136, v139, vcc
	v_rsq_f32_e32 v136, v136
	s_nop 0
	v_mul_f32_e32 v139, 0x45800000, v136
	v_cndmask_b32_e32 v136, v136, v139, vcc
	v_mul_f32_e32 v136, 0x3e000000, v136
	v_add_f32_e32 v138, 0x358637bd, v137
	v_cmp_gt_f32_e32 vcc, s15, v138
	v_mul_f32_e32 v139, 0x4b800000, v138
	s_nop 0
	v_cndmask_b32_e32 v138, v138, v139, vcc
	v_rsq_f32_e32 v138, v138
	s_nop 0
	v_mul_f32_e32 v139, 0x45800000, v138
	v_cndmask_b32_e32 v138, v138, v139, vcc
	v_mul_f32_e32 v138, 0x3e000000, v138
	v_pk_mul_f32 v[144:145], v[144:145], v[136:137] op_sel_hi:[1,0]
	v_pk_mul_f32 v[146:147], v[146:147], v[136:137] op_sel_hi:[1,0]
	v_pk_mul_f32 v[148:149], v[148:149], v[136:137] op_sel_hi:[1,0]
	v_pk_mul_f32 v[150:151], v[150:151], v[136:137] op_sel_hi:[1,0]
	v_pk_mul_f32 v[152:153], v[152:153], v[138:139] op_sel_hi:[1,0]
	v_pk_mul_f32 v[154:155], v[154:155], v[138:139] op_sel_hi:[1,0]
	v_pk_mul_f32 v[156:157], v[156:157], v[138:139] op_sel_hi:[1,0]
	v_pk_mul_f32 v[158:159], v[158:159], v[138:139] op_sel_hi:[1,0]
	v_cvt_pk_bf16_f32 v172, v144, v145
	v_cvt_pk_bf16_f32 v173, v146, v147
	v_cvt_pk_bf16_f32 v174, v148, v149
	v_cvt_pk_bf16_f32 v175, v150, v151
	ds_write_b128 v195, v[172:175] offset:45632
	v_cvt_pk_bf16_f32 v136, v152, v153
	v_cvt_pk_bf16_f32 v137, v154, v155
	v_cvt_pk_bf16_f32 v138, v156, v157
	v_cvt_pk_bf16_f32 v139, v158, v159
	ds_write_b128 v196, v[136:139] offset:45632
	s_waitcnt lgkmcnt(2)
; __device__ __forceinline__ float siluf_(float x) { return x * __builtin_amdgcn_rcpf(1.f + __expf(-x)); }
; __device__ void dn_item(const Params& p, int l, int item, char* smem, int wv) {
;     ...
;       for (int part = 0; part < 3; ++part) {
;         float acc[16];
; #pragma unroll
;         for (int e = 0; e < 16; ++e) acc[e] = 0.f;
; #pragma unroll
;         for (int kb2 = 0; kb2 < 2; ++kb2) {
;           const int k0 = kb2 * 3, nk = kb2 ? 2 : 3;
;           uint4 rv[3][2];
;           float4 wv4[3][4];
; #pragma unroll
;           for (int kq = 0; kq < 3; ++kq) {
;             if (kq < nk) {
;               const int kk = k0 + kq;
;               const u16* rr = R0 + (ti + kk) * RS + part * 64 + dc * 16;
;               rv[kq][0] = *(const uint4*)rr;
;               rv[kq][1] = *(const uint4*)(rr + 8);
;               const float* wp = cw + kk * 192 + part * 64 + dc * 16;
; #pragma unroll
;               for (int e4 = 0; e4 < 4; ++e4) wv4[kq][e4] = *(const float4*)(wp + e4 * 4);
;             }
;           }
;           __builtin_amdgcn_sched_barrier(0);
; #pragma unroll
;           for (int kq = 0; kq < 3; ++kq) {
;             if (kq < nk) {
;               unsigned rw[8] = {rv[kq][0].x, rv[kq][0].y, rv[kq][0].z, rv[kq][0].w, rv[kq][1].x, rv[kq][1].y, rv[kq][1].z, rv[kq][1].w};
; #pragma unroll
;               for (int e4 = 0; e4 < 4; ++e4) {
;                 float4 w = wv4[kq][e4];
;                 acc[e4 * 4 + 0] += w.x * __uint_as_float(rw[e4 * 2] << 16);
;                 acc[e4 * 4 + 1] += w.y * __uint_as_float(rw[e4 * 2] & 0xffff0000u);
;                 acc[e4 * 4 + 2] += w.z * __uint_as_float(rw[e4 * 2 + 1] << 16);
;                 acc[e4 * 4 + 3] += w.w * __uint_as_float(rw[e4 * 2 + 1] & 0xffff0000u);
;               }
;             }
;           }
;           __builtin_amdgcn_sched_barrier(0);
;         }
;         float ss = 0.f;
; #pragma unroll
;         for (int e = 0; e < 16; ++e) { acc[e] = siluf_(acc[e]); ss += acc[e] * acc[e]; }
	v_lshlrev_b32_e32 v122, 16, v30
	v_and_b32_e32 v123, 0xffff0000, v30
	v_lshlrev_b32_e32 v160, 16, v31
	v_and_b32_e32 v161, 0xffff0000, v31
	v_lshlrev_b32_e32 v124, 16, v34
	v_and_b32_e32 v125, 0xffff0000, v34
	v_lshlrev_b32_e32 v162, 16, v35
	v_and_b32_e32 v163, 0xffff0000, v35
	v_lshlrev_b32_e32 v126, 16, v38
	v_and_b32_e32 v127, 0xffff0000, v38
	v_lshlrev_b32_e32 v164, 16, v39
	v_and_b32_e32 v165, 0xffff0000, v39
	v_lshlrev_b32_e32 v128, 16, v42
	v_and_b32_e32 v129, 0xffff0000, v42
	v_lshlrev_b32_e32 v166, 16, v43
	v_and_b32_e32 v167, 0xffff0000, v43
	v_lshlrev_b32_e32 v140, 16, v46
	v_and_b32_e32 v141, 0xffff0000, v46
	v_lshlrev_b32_e32 v168, 16, v47
	v_and_b32_e32 v169, 0xffff0000, v47
	v_lshlrev_b32_e32 v142, 16, v50
	v_and_b32_e32 v143, 0xffff0000, v50
	v_lshlrev_b32_e32 v170, 16, v51
	v_and_b32_e32 v171, 0xffff0000, v51
	v_pk_fma_f32 v[144:145], v[54:55], v[122:123], 0 op_sel_hi:[1,1,0]
	v_pk_fma_f32 v[152:153], v[54:55], v[124:125], 0 op_sel_hi:[1,1,0]
	v_pk_fma_f32 v[146:147], v[56:57], v[160:161], 0 op_sel_hi:[1,1,0]
	v_pk_fma_f32 v[154:155], v[56:57], v[162:163], 0 op_sel_hi:[1,1,0]
	v_pk_fma_f32 v[144:145], v[62:63], v[124:125], v[144:145]
	v_pk_fma_f32 v[152:153], v[62:63], v[126:127], v[152:153]
	v_pk_fma_f32 v[146:147], v[64:65], v[162:163], v[146:147]
	v_pk_fma_f32 v[154:155], v[64:65], v[164:165], v[154:155]
	v_pk_fma_f32 v[144:145], v[70:71], v[126:127], v[144:145]
	v_pk_fma_f32 v[152:153], v[70:71], v[128:129], v[152:153]
	v_pk_fma_f32 v[146:147], v[72:73], v[164:165], v[146:147]
	v_pk_fma_f32 v[154:155], v[72:73], v[166:167], v[154:155]
	v_pk_fma_f32 v[144:145], v[106:107], v[128:129], v[144:145]
	v_pk_fma_f32 v[152:153], v[106:107], v[140:141], v[152:153]
	v_pk_fma_f32 v[146:147], v[108:109], v[166:167], v[146:147]
	v_pk_fma_f32 v[154:155], v[108:109], v[168:169], v[154:155]
	v_pk_fma_f32 v[144:145], v[114:115], v[140:141], v[144:145]
	v_pk_fma_f32 v[152:153], v[114:115], v[142:143], v[152:153]
	v_pk_fma_f32 v[146:147], v[116:117], v[168:169], v[146:147]
	v_pk_fma_f32 v[154:155], v[116:117], v[170:171], v[154:155]
	v_lshlrev_b32_e32 v122, 16, v32
	v_and_b32_e32 v123, 0xffff0000, v32
	v_lshlrev_b32_e32 v160, 16, v33
	v_and_b32_e32 v161, 0xffff0000, v33
	v_lshlrev_b32_e32 v124, 16, v36
	v_and_b32_e32 v125, 0xffff0000, v36
	v_lshlrev_b32_e32 v162, 16, v37
	v_and_b32_e32 v163, 0xffff0000, v37
	v_lshlrev_b32_e32 v126, 16, v40
	v_and_b32_e32 v127, 0xffff0000, v40
	v_lshlrev_b32_e32 v164, 16, v41
	v_and_b32_e32 v165, 0xffff0000, v41
	v_lshlrev_b32_e32 v128, 16, v44
	v_and_b32_e32 v129, 0xffff0000, v44
	v_lshlrev_b32_e32 v166, 16, v45
	v_and_b32_e32 v167, 0xffff0000, v45
	v_lshlrev_b32_e32 v140, 16, v48
	v_and_b32_e32 v141, 0xffff0000, v48
	v_lshlrev_b32_e32 v168, 16, v49
	v_and_b32_e32 v169, 0xffff0000, v49
	v_lshlrev_b32_e32 v142, 16, v52
	v_and_b32_e32 v143, 0xffff0000, v52
	v_lshlrev_b32_e32 v170, 16, v53
	v_and_b32_e32 v171, 0xffff0000, v53
	v_pk_fma_f32 v[148:149], v[58:59], v[122:123], 0 op_sel_hi:[1,1,0]
	v_pk_fma_f32 v[156:157], v[58:59], v[124:125], 0 op_sel_hi:[1,1,0]
	v_pk_fma_f32 v[150:151], v[60:61], v[160:161], 0 op_sel_hi:[1,1,0]
	v_pk_fma_f32 v[158:159], v[60:61], v[162:163], 0 op_sel_hi:[1,1,0]
	v_pk_fma_f32 v[148:149], v[66:67], v[124:125], v[148:149]
	v_pk_fma_f32 v[156:157], v[66:67], v[126:127], v[156:157]
	v_pk_fma_f32 v[150:151], v[68:69], v[162:163], v[150:151]
	v_pk_fma_f32 v[158:159], v[68:69], v[164:165], v[158:159]
	v_pk_fma_f32 v[148:149], v[74:75], v[126:127], v[148:149]
	v_pk_fma_f32 v[156:157], v[74:75], v[128:129], v[156:157]
	v_pk_fma_f32 v[150:151], v[76:77], v[164:165], v[150:151]
	v_pk_fma_f32 v[158:159], v[76:77], v[166:167], v[158:159]
	v_pk_fma_f32 v[148:149], v[110:111], v[128:129], v[148:149]
	v_pk_fma_f32 v[156:157], v[110:111], v[140:141], v[156:157]
	v_pk_fma_f32 v[150:151], v[112:113], v[166:167], v[150:151]
	v_pk_fma_f32 v[158:159], v[112:113], v[168:169], v[158:159]
	v_pk_fma_f32 v[148:149], v[118:119], v[140:141], v[148:149]
	v_pk_fma_f32 v[156:157], v[118:119], v[142:143], v[156:157]
	v_pk_fma_f32 v[150:151], v[120:121], v[168:169], v[150:151]
	v_pk_fma_f32 v[158:159], v[120:121], v[170:171], v[158:159]
	ds_read_b128 v[30:33], v187 offset:256
	ds_read_b128 v[34:37], v187 offset:656
	ds_read_b128 v[38:41], v187 offset:1056
	ds_read_b128 v[42:45], v187 offset:1456
	ds_read_b128 v[46:49], v187 offset:1856
	ds_read_b128 v[50:53], v187 offset:2256
	ds_read_b128 v[54:57], v188 offset:512
	ds_read_b128 v[58:61], v188 offset:528
	ds_read_b128 v[62:65], v188 offset:1280
	ds_read_b128 v[66:69], v188 offset:1296
	ds_read_b128 v[70:73], v188 offset:2048
	ds_read_b128 v[74:77], v188 offset:2064
	ds_read_b128 v[106:109], v188 offset:2816
	ds_read_b128 v[110:113], v188 offset:2832
	ds_read_b128 v[114:117], v188 offset:3584
	ds_read_b128 v[118:121], v188 offset:3600
	v_pk_mul_f32 v[160:161], v[144:145], v[176:177] op_sel_hi:[1,0]
	v_pk_mul_f32 v[162:163], v[146:147], v[176:177] op_sel_hi:[1,0]
	v_pk_mul_f32 v[164:165], v[148:149], v[176:177] op_sel_hi:[1,0]
	v_pk_mul_f32 v[166:167], v[150:151], v[176:177] op_sel_hi:[1,0]
	v_pk_mul_f32 v[168:169], v[152:153], v[176:177] op_sel_hi:[1,0]
	v_pk_mul_f32 v[170:171], v[154:155], v[176:177] op_sel_hi:[1,0]
	v_pk_mul_f32 v[172:173], v[156:157], v[176:177] op_sel_hi:[1,0]
	v_pk_mul_f32 v[174:175], v[158:159], v[176:177] op_sel_hi:[1,0]
	v_exp_f32_e32 v160, v160
	v_exp_f32_e32 v161, v161
	v_exp_f32_e32 v162, v162
	v_exp_f32_e32 v163, v163
	v_exp_f32_e32 v164, v164
	v_exp_f32_e32 v165, v165
	v_exp_f32_e32 v166, v166
	v_exp_f32_e32 v167, v167
	v_exp_f32_e32 v168, v168
	v_exp_f32_e32 v169, v169
	v_exp_f32_e32 v170, v170
	v_exp_f32_e32 v171, v171
; __device__ __forceinline__ u16 f2bf(float f) { return (u16)(pack2(f, 0.f) & 0xffffu); }
; __device__ __forceinline__ float siluf_(float x) { return x * __builtin_amdgcn_rcpf(1.f + __expf(-x)); }
; __device__ void dn_item(const Params& p, int l, int item, char* smem, int wv) {
;     ...
;         float ss = 0.f;
; #pragma unroll
;         for (int e = 0; e < 16; ++e) { acc[e] = siluf_(acc[e]); ss += acc[e] * acc[e]; }
;         float sc = 1.f;
;         if (part < 2) {
;           ss += shx(ss, 1, lane);
;           ss += shx(ss, 2, lane);
;           sc = rsqrtf(ss + 1e-6f) * (part == 0 ? 0.125f : 1.f);
;         }
; #pragma unroll
;         for (int e = 0; e < 16; ++e) acc[e] *= sc;
;         u16* dst = (part == 0 ? Qb : (part == 1 ? Kb : Vb)) + ip * 72 + dc * 16;
;         *(uint4*)dst = make_uint4(pack2(acc[0], acc[1]), pack2(acc[2], acc[3]), pack2(acc[4], acc[5]), pack2(acc[6], acc[7]));
;         *(uint4*)(dst + 8) = make_uint4(pack2(acc[8], acc[9]), pack2(acc[10], acc[11]), pack2(acc[12], acc[13]), pack2(acc[14], acc[15]));
;         if (part == 1) {
; #pragma unroll
;           for (int e = 0; e < 16; ++e) KdT[(dc * 16 + e) * 72 + ip] = f2bf(acc[e] * ekd);
	v_exp_f32_e32 v172, v172
	v_exp_f32_e32 v173, v173
	v_exp_f32_e32 v174, v174
	v_exp_f32_e32 v175, v175
	v_pk_add_f32 v[160:161], v[160:161], v[180:181] op_sel_hi:[1,0]
	v_pk_add_f32 v[162:163], v[162:163], v[180:181] op_sel_hi:[1,0]
	v_pk_add_f32 v[164:165], v[164:165], v[180:181] op_sel_hi:[1,0]
	v_pk_add_f32 v[166:167], v[166:167], v[180:181] op_sel_hi:[1,0]
	v_pk_add_f32 v[168:169], v[168:169], v[180:181] op_sel_hi:[1,0]
	v_pk_add_f32 v[170:171], v[170:171], v[180:181] op_sel_hi:[1,0]
	v_pk_add_f32 v[172:173], v[172:173], v[180:181] op_sel_hi:[1,0]
	v_pk_add_f32 v[174:175], v[174:175], v[180:181] op_sel_hi:[1,0]
	v_rcp_f32_e32 v160, v160
	v_rcp_f32_e32 v161, v161
	v_rcp_f32_e32 v162, v162
	v_rcp_f32_e32 v163, v163
	v_rcp_f32_e32 v164, v164
	v_rcp_f32_e32 v165, v165
	v_rcp_f32_e32 v166, v166
	v_rcp_f32_e32 v167, v167
	v_rcp_f32_e32 v168, v168
	v_rcp_f32_e32 v169, v169
	v_rcp_f32_e32 v170, v170
	v_rcp_f32_e32 v171, v171
	v_rcp_f32_e32 v172, v172
	v_rcp_f32_e32 v173, v173
	v_rcp_f32_e32 v174, v174
	v_rcp_f32_e32 v175, v175
	s_nop 0
	v_pk_mul_f32 v[144:145], v[144:145], v[160:161]
	v_pk_mul_f32 v[146:147], v[146:147], v[162:163]
	v_pk_mul_f32 v[148:149], v[148:149], v[164:165]
	v_pk_mul_f32 v[150:151], v[150:151], v[166:167]
	v_pk_mul_f32 v[152:153], v[152:153], v[168:169]
	v_pk_mul_f32 v[154:155], v[154:155], v[170:171]
	v_pk_mul_f32 v[156:157], v[156:157], v[172:173]
	v_pk_mul_f32 v[158:159], v[158:159], v[174:175]
	v_pk_mul_f32 v[160:161], v[144:145], v[144:145]
	v_pk_mul_f32 v[162:163], v[146:147], v[146:147]
	v_pk_mul_f32 v[164:165], v[148:149], v[148:149]
	v_pk_mul_f32 v[166:167], v[150:151], v[150:151]
	v_pk_mul_f32 v[168:169], v[152:153], v[152:153]
	v_pk_mul_f32 v[170:171], v[154:155], v[154:155]
	v_pk_mul_f32 v[172:173], v[156:157], v[156:157]
	v_pk_mul_f32 v[174:175], v[158:159], v[158:159]
	v_pk_add_f32 v[160:161], v[160:161], v[162:163]
	v_pk_add_f32 v[164:165], v[164:165], v[166:167]
	v_pk_add_f32 v[168:169], v[168:169], v[170:171]
	v_pk_add_f32 v[172:173], v[172:173], v[174:175]
	v_pk_add_f32 v[160:161], v[160:161], v[164:165]
	v_pk_add_f32 v[168:169], v[168:169], v[172:173]
	v_add_f32_e32 v136, v160, v161
	v_add_f32_e32 v138, v168, v169
	s_nop 1
	v_add_f32_dpp v135, v136, v136 quad_perm:[1,0,3,2] row_mask:0xf bank_mask:0xf
	v_add_f32_dpp v137, v138, v138 quad_perm:[1,0,3,2] row_mask:0xf bank_mask:0xf
	s_nop 1
	v_add_f32_dpp v136, v135, v135 quad_perm:[2,3,0,1] row_mask:0xf bank_mask:0xf
	v_add_f32_dpp v138, v137, v137 quad_perm:[2,3,0,1] row_mask:0xf bank_mask:0xf
	s_nop 1
	v_add_f32_dpp v135, v136, v136 row_half_mirror row_mask:0xf bank_mask:0xf
	v_add_f32_dpp v137, v138, v138 row_half_mirror row_mask:0xf bank_mask:0xf
	v_add_f32_e32 v136, 0x358637bd, v135
	v_cmp_gt_f32_e32 vcc, s15, v136
	v_mul_f32_e32 v139, 0x4b800000, v136
	s_nop 0
	v_cndmask_b32_e32 v136, v136, v139, vcc
	v_rsq_f32_e32 v136, v136
	s_nop 0
	v_mul_f32_e32 v139, 0x45800000, v136
	v_cndmask_b32_e32 v136, v136, v139, vcc
	v_add_f32_e32 v138, 0x358637bd, v137
	v_cmp_gt_f32_e32 vcc, s15, v138
	v_mul_f32_e32 v139, 0x4b800000, v138
	s_nop 0
	v_cndmask_b32_e32 v138, v138, v139, vcc
	v_rsq_f32_e32 v138, v138
	s_nop 0
	v_mul_f32_e32 v139, 0x45800000, v138
	v_cndmask_b32_e32 v138, v138, v139, vcc
	v_pk_mul_f32 v[144:145], v[144:145], v[136:137] op_sel_hi:[1,0]
	v_pk_mul_f32 v[146:147], v[146:147], v[136:137] op_sel_hi:[1,0]
	v_pk_mul_f32 v[148:149], v[148:149], v[136:137] op_sel_hi:[1,0]
	v_pk_mul_f32 v[150:151], v[150:151], v[136:137] op_sel_hi:[1,0]
	v_pk_mul_f32 v[152:153], v[152:153], v[138:139] op_sel_hi:[1,0]
	v_pk_mul_f32 v[154:155], v[154:155], v[138:139] op_sel_hi:[1,0]
	v_pk_mul_f32 v[156:157], v[156:157], v[138:139] op_sel_hi:[1,0]
	v_pk_mul_f32 v[158:159], v[158:159], v[138:139] op_sel_hi:[1,0]
	v_pk_mul_f32 v[122:123], v[144:145], v[132:133] op_sel:[0,1] op_sel_hi:[1,1]
	v_pk_mul_f32 v[140:141], v[152:153], v[134:135] op_sel_hi:[1,0]
	v_pk_mul_f32 v[124:125], v[146:147], v[132:133] op_sel:[0,1] op_sel_hi:[1,1]
	v_pk_mul_f32 v[142:143], v[154:155], v[134:135] op_sel_hi:[1,0]
	v_pk_mul_f32 v[126:127], v[148:149], v[132:133] op_sel:[0,1] op_sel_hi:[1,1]
	v_pk_mul_f32 v[160:161], v[156:157], v[134:135] op_sel_hi:[1,0]
	v_pk_mul_f32 v[128:129], v[150:151], v[132:133] op_sel:[0,1] op_sel_hi:[1,1]
	v_pk_mul_f32 v[162:163], v[158:159], v[134:135] op_sel_hi:[1,0]
	v_readlane_b32 s6, v253, 40
	s_cmp_lg_u32 s6, 0
	s_cbranch_scc0 .Lb_kdt_dir1
	v_cvt_pk_bf16_f32 v164, v122, v140
	v_cvt_pk_bf16_f32 v165, v123, v141
	v_cvt_pk_bf16_f32 v166, v124, v142
	v_cvt_pk_bf16_f32 v167, v125, v143
	v_cvt_pk_bf16_f32 v168, v126, v160
	v_cvt_pk_bf16_f32 v169, v127, v161
	v_cvt_pk_bf16_f32 v170, v128, v162
	v_cvt_pk_bf16_f32 v171, v129, v163
	s_branch .Lb_kdt_st
.Lb_kdt_dir1:
	v_cvt_pk_bf16_f32 v164, v140, v122
	v_cvt_pk_bf16_f32 v165, v141, v123
	v_cvt_pk_bf16_f32 v166, v142, v124
	v_cvt_pk_bf16_f32 v167, v143, v125
	v_cvt_pk_bf16_f32 v168, v160, v126
	v_cvt_pk_bf16_f32 v169, v161, v127
	v_cvt_pk_bf16_f32 v170, v162, v128
	v_cvt_pk_bf16_f32 v171, v163, v129
; __device__ __forceinline__ u16 f2bf(float f) { return (u16)(pack2(f, 0.f) & 0xffffu); }
; __device__ void dn_item(const Params& p, int l, int item, char* smem, int wv) {
;     ...
;         for (int kb2 = 0; kb2 < 2; ++kb2) {
;           const int k0 = kb2 * 3, nk = kb2 ? 2 : 3;
;           uint4 rv[3][2];
;           float4 wv4[3][4];
; #pragma unroll
;           for (int kq = 0; kq < 3; ++kq) {
;             if (kq < nk) {
;               const int kk = k0 + kq;
;               const u16* rr = R0 + (ti + kk) * RS + part * 64 + dc * 16;
;               rv[kq][0] = *(const uint4*)rr;
;               rv[kq][1] = *(const uint4*)(rr + 8);
;               const float* wp = cw + kk * 192 + part * 64 + dc * 16;
; #pragma unroll
;               for (int e4 = 0; e4 < 4; ++e4) wv4[kq][e4] = *(const float4*)(wp + e4 * 4);
;             }
;           }
;           __builtin_amdgcn_sched_barrier(0);
; #pragma unroll
;           for (int kq = 0; kq < 3; ++kq) {
;             if (kq < nk) {
;               unsigned rw[8] = {rv[kq][0].x, rv[kq][0].y, rv[kq][0].z, rv[kq][0].w, rv[kq][1].x, rv[kq][1].y, rv[kq][1].z, rv[kq][1].w};
; #pragma unroll
;               for (int e4 = 0; e4 < 4; ++e4) {
;                 float4 w = wv4[kq][e4];
;                 acc[e4 * 4 + 0] += w.x * __uint_as_float(rw[e4 * 2] << 16);
;                 acc[e4 * 4 + 1] += w.y * __uint_as_float(rw[e4 * 2] & 0xffff0000u);
;                 acc[e4 * 4 + 2] += w.z * __uint_as_float(rw[e4 * 2 + 1] << 16);
;                 acc[e4 * 4 + 3] += w.w * __uint_as_float(rw[e4 * 2 + 1] & 0xffff0000u);
;               }
;             }
;           }
;           __builtin_amdgcn_sched_barrier(0);
;     ...
;         u16* dst = (part == 0 ? Qb : (part == 1 ? Kb : Vb)) + ip * 72 + dc * 16;
;         *(uint4*)dst = make_uint4(pack2(acc[0], acc[1]), pack2(acc[2], acc[3]), pack2(acc[4], acc[5]), pack2(acc[6], acc[7]));
;         *(uint4*)(dst + 8) = make_uint4(pack2(acc[8], acc[9]), pack2(acc[10], acc[11]), pack2(acc[12], acc[13]), pack2(acc[14], acc[15]));
;         if (part == 1) {
; #pragma unroll
;           for (int e = 0; e < 16; ++e) KdT[(dc * 16 + e) * 72 + ip] = f2bf(acc[e] * ekd);
.Lb_kdt_st:
	ds_write_b32 v197, v164 offset:0
	ds_write_b32 v197, v165 offset:144
	ds_write_b32 v197, v166 offset:288
	ds_write_b32 v197, v167 offset:432
	ds_write_b32 v197, v168 offset:576
	ds_write_b32 v197, v169 offset:720
	ds_write_b32 v197, v170 offset:864
	ds_write_b32 v197, v171 offset:1008
	v_cvt_pk_bf16_f32 v172, v144, v145
	v_cvt_pk_bf16_f32 v173, v146, v147
	v_cvt_pk_bf16_f32 v174, v148, v149
	v_cvt_pk_bf16_f32 v175, v150, v151
	ds_write_b128 v195, v[172:175] offset:27200
	v_cvt_pk_bf16_f32 v136, v152, v153
	v_cvt_pk_bf16_f32 v137, v154, v155
	v_cvt_pk_bf16_f32 v138, v156, v157
	v_cvt_pk_bf16_f32 v139, v158, v159
	ds_write_b128 v196, v[136:139] offset:27200
	s_waitcnt lgkmcnt(10)
	v_lshlrev_b32_e32 v122, 16, v30
	v_and_b32_e32 v123, 0xffff0000, v30
	v_lshlrev_b32_e32 v160, 16, v31
	v_and_b32_e32 v161, 0xffff0000, v31
	v_lshlrev_b32_e32 v124, 16, v34
	v_and_b32_e32 v125, 0xffff0000, v34
	v_lshlrev_b32_e32 v162, 16, v35
	v_and_b32_e32 v163, 0xffff0000, v35
	v_lshlrev_b32_e32 v126, 16, v38
	v_and_b32_e32 v127, 0xffff0000, v38
	v_lshlrev_b32_e32 v164, 16, v39
	v_and_b32_e32 v165, 0xffff0000, v39
	v_lshlrev_b32_e32 v128, 16, v42
	v_and_b32_e32 v129, 0xffff0000, v42
	v_lshlrev_b32_e32 v166, 16, v43
	v_and_b32_e32 v167, 0xffff0000, v43
	v_lshlrev_b32_e32 v140, 16, v46
	v_and_b32_e32 v141, 0xffff0000, v46
	v_lshlrev_b32_e32 v168, 16, v47
	v_and_b32_e32 v169, 0xffff0000, v47
	v_lshlrev_b32_e32 v142, 16, v50
	v_and_b32_e32 v143, 0xffff0000, v50
	v_lshlrev_b32_e32 v170, 16, v51
	v_and_b32_e32 v171, 0xffff0000, v51
	v_pk_fma_f32 v[144:145], v[54:55], v[122:123], 0 op_sel_hi:[1,1,0]
	v_pk_fma_f32 v[152:153], v[54:55], v[124:125], 0 op_sel_hi:[1,1,0]
	v_pk_fma_f32 v[146:147], v[56:57], v[160:161], 0 op_sel_hi:[1,1,0]
	v_pk_fma_f32 v[154:155], v[56:57], v[162:163], 0 op_sel_hi:[1,1,0]
	v_pk_fma_f32 v[144:145], v[62:63], v[124:125], v[144:145]
	v_pk_fma_f32 v[152:153], v[62:63], v[126:127], v[152:153]
	v_pk_fma_f32 v[146:147], v[64:65], v[162:163], v[146:147]
	v_pk_fma_f32 v[154:155], v[64:65], v[164:165], v[154:155]
	v_pk_fma_f32 v[144:145], v[70:71], v[126:127], v[144:145]
	v_pk_fma_f32 v[152:153], v[70:71], v[128:129], v[152:153]
	v_pk_fma_f32 v[146:147], v[72:73], v[164:165], v[146:147]
	v_pk_fma_f32 v[154:155], v[72:73], v[166:167], v[154:155]
	v_pk_fma_f32 v[144:145], v[106:107], v[128:129], v[144:145]
	v_pk_fma_f32 v[152:153], v[106:107], v[140:141], v[152:153]
	v_pk_fma_f32 v[146:147], v[108:109], v[166:167], v[146:147]
	v_pk_fma_f32 v[154:155], v[108:109], v[168:169], v[154:155]
	v_pk_fma_f32 v[144:145], v[114:115], v[140:141], v[144:145]
	v_pk_fma_f32 v[152:153], v[114:115], v[142:143], v[152:153]
	v_pk_fma_f32 v[146:147], v[116:117], v[168:169], v[146:147]
	v_pk_fma_f32 v[154:155], v[116:117], v[170:171], v[154:155]
	v_lshlrev_b32_e32 v122, 16, v32
	v_and_b32_e32 v123, 0xffff0000, v32
	v_lshlrev_b32_e32 v160, 16, v33
	v_and_b32_e32 v161, 0xffff0000, v33
	v_lshlrev_b32_e32 v124, 16, v36
	v_and_b32_e32 v125, 0xffff0000, v36
	v_lshlrev_b32_e32 v162, 16, v37
	v_and_b32_e32 v163, 0xffff0000, v37
	v_lshlrev_b32_e32 v126, 16, v40
	v_and_b32_e32 v127, 0xffff0000, v40
	v_lshlrev_b32_e32 v164, 16, v41
	v_and_b32_e32 v165, 0xffff0000, v41
	v_lshlrev_b32_e32 v128, 16, v44
	v_and_b32_e32 v129, 0xffff0000, v44
	v_lshlrev_b32_e32 v166, 16, v45
	v_and_b32_e32 v167, 0xffff0000, v45
	v_lshlrev_b32_e32 v140, 16, v48
	v_and_b32_e32 v141, 0xffff0000, v48
	v_lshlrev_b32_e32 v168, 16, v49
	v_and_b32_e32 v169, 0xffff0000, v49
	v_lshlrev_b32_e32 v142, 16, v52
	v_and_b32_e32 v143, 0xffff0000, v52
	v_lshlrev_b32_e32 v170, 16, v53
	v_and_b32_e32 v171, 0xffff0000, v53
	v_pk_fma_f32 v[148:149], v[58:59], v[122:123], 0 op_sel_hi:[1,1,0]
	v_pk_fma_f32 v[156:157], v[58:59], v[124:125], 0 op_sel_hi:[1,1,0]
	v_pk_fma_f32 v[150:151], v[60:61], v[160:161], 0 op_sel_hi:[1,1,0]
	v_pk_fma_f32 v[158:159], v[60:61], v[162:163], 0 op_sel_hi:[1,1,0]
	v_pk_fma_f32 v[148:149], v[66:67], v[124:125], v[148:149]
	v_pk_fma_f32 v[156:157], v[66:67], v[126:127], v[156:157]
	v_pk_fma_f32 v[150:151], v[68:69], v[162:163], v[150:151]
	v_pk_fma_f32 v[158:159], v[68:69], v[164:165], v[158:159]
	v_pk_fma_f32 v[148:149], v[74:75], v[126:127], v[148:149]
	v_pk_fma_f32 v[156:157], v[74:75], v[128:129], v[156:157]
	v_pk_fma_f32 v[150:151], v[76:77], v[164:165], v[150:151]
	v_pk_fma_f32 v[158:159], v[76:77], v[166:167], v[158:159]
	v_pk_fma_f32 v[148:149], v[110:111], v[128:129], v[148:149]
	v_pk_fma_f32 v[156:157], v[110:111], v[140:141], v[156:157]
	v_pk_fma_f32 v[150:151], v[112:113], v[166:167], v[150:151]
	v_pk_fma_f32 v[158:159], v[112:113], v[168:169], v[158:159]
	v_pk_fma_f32 v[148:149], v[118:119], v[140:141], v[148:149]
	v_pk_fma_f32 v[156:157], v[118:119], v[142:143], v[156:157]
; __device__ __forceinline__ u16 f2bf(float f) { return (u16)(pack2(f, 0.f) & 0xffffu); }
; __device__ __forceinline__ float siluf_(float x) { return x * __builtin_amdgcn_rcpf(1.f + __expf(-x)); }
; __device__ void dn_item(const Params& p, int l, int item, char* smem, int wv) {
;     ...
;   auto prefetch = [&](int step) {
;     size_t gbase; int tb, Ls;
;     chunk_info(step, gbase, tb, Ls);
;     int tl = tid;
;     asm volatile("" : "+v"(tl));
;     const int rr = tl / 24, seg = tl - rr * 24, part = seg >> 3, s8 = seg & 7;
;     const u16* src = P + (gbase + tb - 2 + rr) * PS + C_QB + part * 384 + h * 64 + s8 * 8;
; #pragma unroll
;     for (int q = 0; q < 7; ++q) {
;       int r = rr + 10 * q;
;       int t = tb - 2 + r;
;       uint4 val = make_uint4(0, 0, 0, 0);
;       if (tl < 240 && r < 68 && t >= 0 && t < Ls) val = *(const uint4*)(src + (size_t)(10 * q) * PS);
;     ...
;         float ss = 0.f;
; #pragma unroll
;         for (int e = 0; e < 16; ++e) { acc[e] = siluf_(acc[e]); ss += acc[e] * acc[e]; }
;         float sc = 1.f;
;         if (part < 2) {
;           ss += shx(ss, 1, lane);
;           ss += shx(ss, 2, lane);
;           sc = rsqrtf(ss + 1e-6f) * (part == 0 ? 0.125f : 1.f);
;         }
; #pragma unroll
;         for (int e = 0; e < 16; ++e) acc[e] *= sc;
;         u16* dst = (part == 0 ? Qb : (part == 1 ? Kb : Vb)) + ip * 72 + dc * 16;
;         *(uint4*)dst = make_uint4(pack2(acc[0], acc[1]), pack2(acc[2], acc[3]), pack2(acc[4], acc[5]), pack2(acc[6], acc[7]));
;         *(uint4*)(dst + 8) = make_uint4(pack2(acc[8], acc[9]), pack2(acc[10], acc[11]), pack2(acc[12], acc[13]), pack2(acc[14], acc[15]));
;         if (part == 1) {
; #pragma unroll
;           for (int e = 0; e < 16; ++e) KdT[(dc * 16 + e) * 72 + ip] = f2bf(acc[e] * ekd);
;         }
;       }
;     }
;     lds_barrier();
;     if (step + 1 < 68) prefetch(step + 1);
	v_pk_fma_f32 v[150:151], v[120:121], v[168:169], v[150:151]
	v_pk_fma_f32 v[158:159], v[120:121], v[170:171], v[158:159]
	v_pk_mul_f32 v[160:161], v[144:145], v[176:177] op_sel_hi:[1,0]
	v_pk_mul_f32 v[162:163], v[146:147], v[176:177] op_sel_hi:[1,0]
	v_pk_mul_f32 v[164:165], v[148:149], v[176:177] op_sel_hi:[1,0]
	v_pk_mul_f32 v[166:167], v[150:151], v[176:177] op_sel_hi:[1,0]
	v_pk_mul_f32 v[168:169], v[152:153], v[176:177] op_sel_hi:[1,0]
	v_pk_mul_f32 v[170:171], v[154:155], v[176:177] op_sel_hi:[1,0]
	v_pk_mul_f32 v[172:173], v[156:157], v[176:177] op_sel_hi:[1,0]
	v_pk_mul_f32 v[174:175], v[158:159], v[176:177] op_sel_hi:[1,0]
	v_exp_f32_e32 v160, v160
	v_exp_f32_e32 v161, v161
	v_exp_f32_e32 v162, v162
	v_exp_f32_e32 v163, v163
	v_exp_f32_e32 v164, v164
	v_exp_f32_e32 v165, v165
	v_exp_f32_e32 v166, v166
	v_exp_f32_e32 v167, v167
	v_exp_f32_e32 v168, v168
	v_exp_f32_e32 v169, v169
	v_exp_f32_e32 v170, v170
	v_exp_f32_e32 v171, v171
	v_exp_f32_e32 v172, v172
	v_exp_f32_e32 v173, v173
	v_exp_f32_e32 v174, v174
	v_exp_f32_e32 v175, v175
	v_pk_add_f32 v[160:161], v[160:161], v[180:181] op_sel_hi:[1,0]
	v_pk_add_f32 v[162:163], v[162:163], v[180:181] op_sel_hi:[1,0]
	v_pk_add_f32 v[164:165], v[164:165], v[180:181] op_sel_hi:[1,0]
	v_pk_add_f32 v[166:167], v[166:167], v[180:181] op_sel_hi:[1,0]
	v_pk_add_f32 v[168:169], v[168:169], v[180:181] op_sel_hi:[1,0]
	v_pk_add_f32 v[170:171], v[170:171], v[180:181] op_sel_hi:[1,0]
	v_pk_add_f32 v[172:173], v[172:173], v[180:181] op_sel_hi:[1,0]
	v_pk_add_f32 v[174:175], v[174:175], v[180:181] op_sel_hi:[1,0]
	v_rcp_f32_e32 v160, v160
	v_rcp_f32_e32 v161, v161
	v_rcp_f32_e32 v162, v162
	v_rcp_f32_e32 v163, v163
	v_rcp_f32_e32 v164, v164
	v_rcp_f32_e32 v165, v165
	v_rcp_f32_e32 v166, v166
	v_rcp_f32_e32 v167, v167
	v_rcp_f32_e32 v168, v168
	v_rcp_f32_e32 v169, v169
	v_rcp_f32_e32 v170, v170
	v_rcp_f32_e32 v171, v171
	v_rcp_f32_e32 v172, v172
	v_rcp_f32_e32 v173, v173
	v_rcp_f32_e32 v174, v174
	v_rcp_f32_e32 v175, v175
	s_nop 0
	v_pk_mul_f32 v[144:145], v[144:145], v[160:161]
	v_pk_mul_f32 v[146:147], v[146:147], v[162:163]
	v_pk_mul_f32 v[148:149], v[148:149], v[164:165]
	v_pk_mul_f32 v[150:151], v[150:151], v[166:167]
	v_pk_mul_f32 v[152:153], v[152:153], v[168:169]
	v_pk_mul_f32 v[154:155], v[154:155], v[170:171]
	v_pk_mul_f32 v[156:157], v[156:157], v[172:173]
	v_pk_mul_f32 v[158:159], v[158:159], v[174:175]
	v_cvt_pk_bf16_f32 v172, v144, v145
	v_cvt_pk_bf16_f32 v173, v146, v147
	v_cvt_pk_bf16_f32 v174, v148, v149
	v_cvt_pk_bf16_f32 v175, v150, v151
	ds_write_b128 v195, v[172:175] offset:36416
	v_cvt_pk_bf16_f32 v136, v152, v153
	v_cvt_pk_bf16_f32 v137, v154, v155
	v_cvt_pk_bf16_f32 v138, v156, v157
	v_cvt_pk_bf16_f32 v139, v158, v159
	ds_write_b128 v196, v[136:139] offset:36416
	s_cmp_lg_u32 s42, 63
	s_cselect_b64 s[38:39], -1, 0
	s_cmp_eq_u32 s42, 63
	s_waitcnt lgkmcnt(0)
	s_barrier
	s_cbranch_scc1 .LBB0_357
	s_add_i32 s6, s42, 5
	s_add_i32 s7, s42, 1
	s_cmp_lt_u32 s43, 3
	s_movk_i32 s36, 0x1000
	s_cselect_b32 s77, 0x100, s36
	v_readlane_b32 s36, v253, 51
	s_cselect_b32 s40, s6, s7
	v_readlane_b32 s7, v253, 44
	v_readlane_b32 s37, v253, 52
	s_cselect_b32 s6, 3, 63
	s_cselect_b32 s37, s7, s37
	v_readlane_b32 s7, v253, 43
	s_cselect_b32 s36, s7, s36
	s_sub_i32 s41, s6, s40
	v_readlane_b32 s6, v253, 40
	v_readlane_b32 s7, v253, 41
	s_and_b64 s[6:7], s[6:7], exec
	s_cselect_b32 s6, s40, s41
	s_lshl_b32 s76, s6, 6
	s_waitcnt vmcnt(0)
	v_mov_b32_e32 v26, v78
	s_mov_b32 s6, 0x2aaaaaab
	v_mov_b64_e32 v[6:7], s[18:19]
	v_mul_hi_i32 v0, v26, s6
	v_lshrrev_b32_e32 v2, 31, v0
	v_ashrrev_i32_e32 v0, 2, v0
	v_add_u32_e32 v2, v0, v2
	s_movk_i32 s6, 0xffe8
	v_mad_u64_u32 v[4:5], s[6:7], v2, s6, v[26:27]
	s_ashr_i32 s6, s76, 31
	s_add_u32 s7, s36, s76
	s_addc_u32 s40, s37, s6
	s_add_u32 s6, s7, -2
	v_ashrrev_i32_e32 v3, 31, v2
	s_addc_u32 s7, s40, -1
	v_lshrrev_b32_e32 v0, 3, v4
	v_lshl_add_u64 v[4:5], s[6:7], 0, v[2:3]
	v_mad_u64_u32 v[6:7], s[6:7], v4, s71, v[6:7]
	s_movk_i32 s6, 0x180
	s_nop 0
	v_mul_lo_u32 v4, v0, s6
	v_mad_i32_i24 v7, v5, s71, v7
	v_ashrrev_i32_e32 v5, 31, v4
	v_readlane_b32 s6, v253, 56
	v_lshl_add_u64 v[4:5], v[4:5], 1, v[6:7]
	v_readlane_b32 s7, v253, 57
	v_lshlrev_b32_e32 v0, 4, v26
	v_add3_u32 v27, s76, -2, v2
	v_lshl_add_u64 v[4:5], s[6:7], 1, v[4:5]
	s_movk_i32 s6, 0xf0
	v_and_b32_e32 v0, 0x70, v0
	v_cmp_gt_i32_e64 s[6:7], s6, v26
	v_cmp_gt_u32_e32 vcc, s77, v27
	v_mov_b32_e32 v6, v1
	v_mov_b32_e32 v7, v1
	v_lshl_add_u64 v[8:9], v[4:5], 0, v[0:1]
	s_and_b64 vcc, s[6:7], vcc
	v_mov_b64_e32 v[2:3], v[6:7]
	v_mov_b64_e32 v[4:5], v[6:7]
	s_and_saveexec_b64 s[40:41], vcc
	s_cbranch_execz .LBB0_342
	global_load_dwordx4 v[2:5], v[8:9], off offset:1536

; __device__ void dn_item(const Params& p, int l, int item, char* smem, int wv) {
;     ...
;       const int i0 = 16 * wave + fq * 4;
;       bf16x8 ka[2], qa[2], kbt[2][4];
;       float gi[4], bi[4], gj[4];
;       u16 vraw[4][4];
; #pragma unroll
;       for (int kk = 0; kk < 2; ++kk) {
;         ka[kk] = *(const bf16x8*)(Kb + (16 * wave + fr) * 72 + kk * 32 + fq * 8);
;         qa[kk] = *(const bf16x8*)(Qb + (16 * wave + fr) * 72 + kk * 32 + fq * 8);
; #pragma unroll
;         for (int n = 0; n < 4; ++n) kbt[kk][n] = *(const bf16x8*)(Kb + (n * 16 + fr) * 72 + kk * 32 + fq * 8);
;       }
;       __builtin_amdgcn_sched_barrier(0);
;       f32x4 kk4[4], qk[4];
; #pragma unroll
;       for (int n = 0; n < 4; ++n) {
;         kk4[n] = (f32x4){0.f, 0.f, 0.f, 0.f};
;         qk[n] = (f32x4){0.f, 0.f, 0.f, 0.f};
;         rhs[n] = (f32x4){0.f, 0.f, 0.f, 0.f};
;       }
; #pragma unroll
;       for (int kk = 0; kk < 2; ++kk)
; #pragma unroll
;         for (int n = 0; n < 4; ++n) {
;           kk4[n] = mfma16(ka[kk], kbt[kk][n], kk4[n]);
;           qk[n] = mfma16(qa[kk], kbt[kk][n], qk[n]);
;         }
;       __builtin_amdgcn_sched_barrier(0);
;       {
;         bf16x8 sbt[2][4];
; #pragma unroll
;         for (int kk = 0; kk < 2; ++kk)
; #pragma unroll
;           for (int n = 0; n < 4; ++n) sbt[kk][n] = *(const bf16x8*)(Stb + (n * 16 + fr) * 72 + kk * 32 + fq * 8);
; #pragma unroll
;         for (int j = 0; j < 4; ++j) { gi[j] = gcs[i0 + j]; bi[j] = bts[i0 + j]; gj[j] = gcs[j * 16 + fr]; }
; #pragma unroll
;         for (int n = 0; n < 4; ++n)
; #pragma unroll
;           for (int j = 0; j < 4; ++j) vraw[n][j] = Vb[(i0 + j) * 72 + n * 16 + fr];
;         __builtin_amdgcn_sched_barrier(0);
; #pragma unroll
;         for (int kk = 0; kk < 2; ++kk)
; #pragma unroll
;           for (int n = 0; n < 4; ++n) rhs[n] = mfma16(ka[kk], sbt[kk][n], rhs[n]);
;       }
;       float eg[4];
; #pragma unroll
;       for (int j = 0; j < 4; ++j) eg[j] = __expf(gi[j]);
; #pragma unroll
;       for (int n = 0; n < 4; ++n) {
;         const int jj = n * 16 + fr;
;         float lv[4];
; #pragma unroll
;         for (int j = 0; j < 4; ++j) {
;           int i = i0 + j;
;           float e = (i >= jj) ? __expf(gi[j] - gj[n]) : 0.f;
;           lv[j] = (i > jj) ? bi[j] * kk4[n][j] * e : 0.f;
;           Ib[i * 72 + jj] = f2bf(qk[n][j] * e);
.LBB0_357:
	v_add_u32_e32 v0, v80, v87
	ds_read_b128 v[50:53], v82 offset:27200
	ds_read_b128 v[64:67], v82 offset:27264
	ds_read_b128 v[30:33], v82 offset:45632
	ds_read_b128 v[58:61], v82 offset:45696
	ds_read_b128 v[34:37], v0 offset:27200
	ds_read_b128 v[38:41], v0 offset:27264
	ds_read_b128 v[42:45], v0 offset:29504
	ds_read_b128 v[46:49], v0 offset:29568
	ds_read_b128 v[54:57], v0 offset:31808
	ds_read_b128 v[68:71], v0 offset:31872
	ds_read_b128 v[72:75], v0 offset:34112
	ds_read_b128 v[106:109], v0 offset:34176
	s_waitcnt lgkmcnt(7)
	v_mfma_f32_16x16x32_bf16 v[110:113], v[50:53], v[34:37], 0
	v_mfma_f32_16x16x32_bf16 v[34:37], v[30:33], v[34:37], 0
	s_waitcnt lgkmcnt(5)
	v_mfma_f32_16x16x32_bf16 v[114:117], v[50:53], v[42:45], 0
	v_mfma_f32_16x16x32_bf16 v[42:45], v[30:33], v[42:45], 0
	s_waitcnt lgkmcnt(3)
	v_mfma_f32_16x16x32_bf16 v[118:121], v[50:53], v[54:57], 0
	v_mfma_f32_16x16x32_bf16 v[122:125], v[30:33], v[54:57], 0
	s_waitcnt lgkmcnt(1)
	v_mfma_f32_16x16x32_bf16 v[126:129], v[50:53], v[72:75], 0
	v_mfma_f32_16x16x32_bf16 v[30:33], v[30:33], v[72:75], 0
	v_mfma_f32_16x16x32_bf16 v[72:75], v[64:67], v[38:41], v[110:113]
	v_mfma_f32_16x16x32_bf16 v[110:113], v[58:61], v[38:41], v[34:37]
	v_mfma_f32_16x16x32_bf16 v[54:57], v[64:67], v[46:49], v[114:117]
	v_mfma_f32_16x16x32_bf16 v[46:49], v[58:61], v[46:49], v[42:45]
	v_mfma_f32_16x16x32_bf16 v[42:45], v[64:67], v[68:71], v[118:121]
	v_mfma_f32_16x16x32_bf16 v[38:41], v[58:61], v[68:71], v[122:125]
	s_waitcnt lgkmcnt(0)
	v_mfma_f32_16x16x32_bf16 v[34:37], v[64:67], v[106:109], v[126:129]
	v_mfma_f32_16x16x32_bf16 v[30:33], v[58:61], v[106:109], v[30:33]
	v_add_u32_e32 v62, v83, v87
	ds_read_b128 v[58:61], v62 offset:64064
	ds_read_b128 v[68:71], v62 offset:64128
	v_add_u32_e32 v63, v83, v89
	v_add_u32_e32 v62, v83, v203
	ds_read_b128 v[106:109], v63 offset:64064
	ds_read_b128 v[114:117], v63 offset:64128
	ds_read_b128 v[118:121], v62 offset:64064
	ds_read_b128 v[122:125], v62 offset:64128
	v_add_u32_e32 v63, v83, v204
	s_waitcnt lgkmcnt(5)
	v_mfma_f32_16x16x32_bf16 v[58:61], v[50:53], v[58:61], 0
	ds_read_b128 v[126:129], v63 offset:64064
	ds_read_b128 v[132:135], v63 offset:64128
	v_add_u32_e32 v250, v190, v214
	v_readlane_b32 s6, v254, 48
	s_waitcnt lgkmcnt(5)
	v_mfma_f32_16x16x32_bf16 v[106:109], v[50:53], v[106:109], 0
	v_readlane_b32 s7, v254, 49
	v_add_u32_e32 v249, v190, v215
	v_add_u32_e32 v248, v190, v216
	s_waitcnt lgkmcnt(3)
	v_mfma_f32_16x16x32_bf16 v[118:121], v[50:53], v[118:121], 0
	s_waitcnt lgkmcnt(1)
	v_mfma_f32_16x16x32_bf16 v[50:53], v[50:53], v[126:129], 0
	v_mfma_f32_16x16x32_bf16 v[68:71], v[64:67], v[68:71], v[58:61]
	s_nop 2
	ds_read_b64 v[60:61], v205
	ds_read_b64 v[58:59], v206
	ds_read_b32 v76, v207
	ds_read_b32 v77, v208
	ds_read_b32 v126, v210
	ds_read_b32 v127, v212
	ds_read_b32 v128, v213
	ds_read_b64 v[62:63], v211
	ds_read_b32 v129, v209
	v_mfma_f32_16x16x32_bf16 v[106:109], v[64:67], v[114:117], v[106:109]
	v_mfma_f32_16x16x32_bf16 v[114:117], v[64:67], v[122:125], v[118:121]
	s_waitcnt lgkmcnt(9)
	v_mfma_f32_16x16x32_bf16 v[50:53], v[64:67], v[132:135], v[50:53]
	s_waitcnt lgkmcnt(6)
	v_sub_f32_e32 v65, v60, v76
	v_mul_f32_e32 v65, 0x3fb8aa3b, v65
	v_mul_f32_e32 v64, 0x3fb8aa3b, v60
	v_exp_f32_e32 v65, v65
	v_exp_f32_e32 v118, v64
	v_mul_f32_e32 v64, 0x3fb8aa3b, v61
	v_exp_f32_e32 v119, v64
	s_waitcnt lgkmcnt(4)
	v_mul_f32_e32 v64, 0x3fb8aa3b, v126
	v_exp_f32_e32 v120, v64
	s_waitcnt lgkmcnt(3)
	v_mul_f32_e32 v64, 0x3fb8aa3b, v127
	v_exp_f32_e32 v121, v64
	v_cndmask_b32_e64 v65, v65, 0, s[50:51]
	v_mul_f32_e32 v64, v72, v58
	v_mul_f32_e32 v64, v64, v65
	v_mul_f32_e32 v65, v110, v65
	v_cvt_pk_bf16_f32 v66, v65, s0
	v_sub_f32_e32 v65, v61, v76
	v_mul_f32_e32 v65, 0x3fb8aa3b, v65
	v_exp_f32_e32 v65, v65
	ds_read_u16 v67, v250 offset:36416
	ds_read_u16 v72, v250 offset:36448
	ds_read_u16 v110, v250 offset:36560
	ds_read_u16 v122, v250 offset:36592
	ds_read_u16 v123, v250 offset:36480
	ds_read_u16 v124, v250 offset:36624
	ds_read_u16 v125, v250 offset:36656
	ds_read_u16 v132, v250 offset:36512
	s_waitcnt lgkmcnt(7)
	v_lshlrev_b32_e32 v67, 16, v67
	v_cndmask_b32_e64 v64, 0, v64, s[6:7]
	v_fma_f32 v67, -v118, v68, v67
	v_readlane_b32 s6, v254, 50
	s_waitcnt lgkmcnt(5)
	v_lshlrev_b32_e32 v68, 16, v110
	v_readlane_b32 s7, v254, 51
	v_fma_f32 v68, -v119, v69, v68
	v_mul_f32_e32 v133, v58, v67
	v_cndmask_b32_e64 v67, v65, 0, s[6:7]
	v_mul_f32_e32 v65, v73, v59
	v_mul_f32_e32 v73, v59, v68
	v_sub_f32_e32 v68, v126, v76
	v_sub_f32_e32 v76, v127, v76
	v_mul_f32_e32 v68, 0x3fb8aa3b, v68
	v_mul_f32_e32 v76, 0x3fb8aa3b, v76
	v_mul_f32_e32 v65, v65, v67
	v_mul_f32_e32 v67, v111, v67
	v_exp_f32_e32 v68, v68
	ds_read_u16 v69, v249 offset:36416
	ds_read_u16 v110, v249 offset:36448
	ds_read_u16 v111, v248 offset:36416
	ds_read_u16 v134, v248 offset:36448
	ds_read_u16 v135, v249 offset:36480
	ds_read_u16 v136, v248 offset:36480
	ds_read_u16 v137, v248 offset:36512
	ds_read_u16 v138, v249 offset:36512
	v_exp_f32_e32 v76, v76
	s_waitcnt lgkmcnt(7)
	v_lshlrev_b32_e32 v69, 16, v69
	v_fma_f32 v70, -v120, v70, v69
	s_waitcnt lgkmcnt(5)
; __device__ __forceinline__ u16 f2bf(float f) { return (u16)(pack2(f, 0.f) & 0xffffu); }
; __device__ __forceinline__ float bf2f(u16 h) { return __uint_as_float(((unsigned)h) << 16); }
; __device__ void dn_item(const Params& p, int l, int item, char* smem, int wv) {
;     ...
;       float eg[4];
; #pragma unroll
;       for (int j = 0; j < 4; ++j) eg[j] = __expf(gi[j]);
; #pragma unroll
;       for (int n = 0; n < 4; ++n) {
;         const int jj = n * 16 + fr;
;         float lv[4];
; #pragma unroll
;         for (int j = 0; j < 4; ++j) {
;           int i = i0 + j;
;           float e = (i >= jj) ? __expf(gi[j] - gj[n]) : 0.f;
;           lv[j] = (i > jj) ? bi[j] * kk4[n][j] * e : 0.f;
;           Ib[i * 72 + jj] = f2bf(qk[n][j] * e);
;           rhs[n][j] = bi[j] * (bf2f(vraw[n][j]) - eg[j] * rhs[n][j]);
;         }
;         *(float4*)(LfT + jj * 68 + i0) = make_float4(lv[0], lv[1], lv[2], lv[3]);
;       }
;     }
;     lds_barrier();
	v_lshlrev_b32_e32 v69, 16, v111
	v_cndmask_b32_e64 v65, v65, 0, s[50:51]
	v_cvt_pk_bf16_f32 v67, v67, s0
	v_fma_f32 v71, -v121, v71, v69
	v_readlane_b32 s6, v254, 52
	v_readlane_b32 s7, v254, 53
	v_add_u32_e32 v111, v217, v214
	ds_write_b16 v111, v66 offset:17408
	ds_write_b16 v111, v67 offset:17552
	v_cndmask_b32_e64 v69, v76, 0, s[6:7]
	v_readlane_b32 s6, v254, 54
	v_readlane_b32 s7, v254, 55
	v_add_u32_e32 v76, v217, v215
	v_mul_f32_e32 v54, v54, v58
	v_cndmask_b32_e64 v68, v68, 0, s[6:7]
	v_mul_f32_e32 v66, v112, v68
	v_cvt_pk_bf16_f32 v66, v66, s0
	ds_write_b16 v76, v66 offset:17408
	v_pk_mul_f32 v[66:67], v[74:75], v[62:63]
	v_sub_f32_e32 v74, v60, v77
	v_readlane_b32 s6, v254, 56
	v_mul_f32_e32 v74, 0x3fb8aa3b, v74
	v_pk_mul_f32 v[66:67], v[66:67], v[68:69]
	v_readlane_b32 s7, v254, 57
	v_exp_f32_e32 v74, v74
	v_mul_f32_e32 v68, v113, v69
	v_cndmask_b32_e64 v67, 0, v67, s[6:7]
	v_readlane_b32 s6, v254, 58
	v_readlane_b32 s7, v254, 59
	v_cvt_pk_bf16_f32 v68, v68, s0
	v_add_u32_e32 v69, v217, v216
	v_cndmask_b32_e64 v66, 0, v66, s[6:7]
	ds_write_b16 v69, v68 offset:17408
	ds_write_b128 v240, v[64:67]
	v_cndmask_b32_e64 v64, v74, 0, s[64:65]
	v_mul_f32_e32 v46, v46, v64
	v_cvt_pk_bf16_f32 v46, v46, s0
	ds_write_b16 v111, v46 offset:17440
	v_sub_f32_e32 v46, v61, v77
	v_mul_f32_e32 v46, 0x3fb8aa3b, v46
	v_readlane_b32 s6, v254, 60
	v_exp_f32_e32 v46, v46
	v_mul_f32_e32 v54, v54, v64
	v_readlane_b32 s7, v254, 61
	v_mul_f32_e32 v55, v55, v59
	v_pk_mul_f32 v[56:57], v[56:57], v[62:63]
	v_cndmask_b32_e64 v54, 0, v54, s[6:7]
	v_readlane_b32 s6, v254, 62
	v_readlane_b32 s7, v254, 63
	v_mul_f32_e32 v43, v43, v59
	v_pk_mul_f32 v[44:45], v[44:45], v[62:63]
	v_cndmask_b32_e64 v46, v46, 0, s[6:7]
	v_mul_f32_e32 v55, v55, v46
	v_mul_f32_e32 v46, v47, v46
	v_lshlrev_b32_e32 v47, 16, v110
	v_cvt_pk_bf16_f32 v46, v46, s0
	v_fma_f32 v47, -v120, v108, v47
	ds_write_b16 v111, v46 offset:17584
	v_lshlrev_b32_e32 v46, 16, v122
	v_mul_f32_e32 v66, v62, v47
	v_sub_f32_e32 v47, v127, v77
	v_fma_f32 v46, -v119, v107, v46
	v_mul_f32_e32 v47, 0x3fb8aa3b, v47
	v_mul_f32_e32 v65, v59, v46
	v_sub_f32_e32 v46, v126, v77
	v_exp_f32_e32 v47, v47
	v_mul_f32_e32 v46, 0x3fb8aa3b, v46
	v_exp_f32_e32 v46, v46
	v_readlane_b32 s6, v255, 0
	v_readlane_b32 s7, v255, 1
	v_cndmask_b32_e64 v55, v55, 0, s[64:65]
	v_mul_f32_e32 v42, v42, v58
	v_cndmask_b32_e64 v47, v47, 0, s[6:7]
	v_readlane_b32 s6, v255, 2
	v_readlane_b32 s7, v255, 3
	v_mul_f32_e32 v35, v35, v59
	v_pk_mul_f32 v[36:37], v[36:37], v[62:63]
	v_cndmask_b32_e64 v46, v46, 0, s[6:7]
	v_mul_f32_e32 v48, v48, v46
	v_pk_mul_f32 v[56:57], v[56:57], v[46:47]
	v_mul_f32_e32 v46, v49, v47
	v_sub_f32_e32 v47, v60, v129
	v_mul_f32_e32 v47, 0x3fb8aa3b, v47
	v_readlane_b32 s6, v255, 4
	v_exp_f32_e32 v47, v47
	v_readlane_b32 s7, v255, 5
	v_cvt_pk_bf16_f32 v48, v48, s0
	v_cvt_pk_bf16_f32 v46, v46, s0
	v_cndmask_b32_e64 v57, 0, v57, s[6:7]
	v_readlane_b32 s6, v255, 6
	v_readlane_b32 s7, v255, 7
	ds_write_b16 v76, v48 offset:17440
	v_mul_f32_e32 v34, v34, v58
	v_cndmask_b32_e64 v56, 0, v56, s[6:7]
	ds_write_b16 v69, v46 offset:17440
	ds_write_b128 v240, v[54:57] offset:4352
	v_cndmask_b32_e64 v46, v47, 0, s[78:79]
	v_mul_f32_e32 v38, v38, v46
	v_cvt_pk_bf16_f32 v38, v38, s0
	ds_write_b16 v111, v38 offset:17472
	v_sub_f32_e32 v38, v61, v129
	v_mul_f32_e32 v38, 0x3fb8aa3b, v38
	v_exp_f32_e32 v38, v38
	v_mul_f32_e32 v42, v42, v46
	v_cndmask_b32_e64 v42, 0, v42, s[80:81]
	v_lshlrev_b32_e32 v64, 16, v72
	v_cndmask_b32_e64 v38, v38, 0, s[82:83]
	v_mul_f32_e32 v43, v43, v38
	v_mul_f32_e32 v38, v39, v38
	v_cvt_pk_bf16_f32 v38, v38, s0
	ds_write_b16 v111, v38 offset:17616
	v_lshlrev_b32_e32 v38, 16, v124
	s_waitcnt lgkmcnt(14)
	v_lshlrev_b32_e32 v39, 16, v135
	v_fma_f32 v38, -v119, v115, v38
	v_fma_f32 v39, -v120, v116, v39
	v_mul_f32_e32 v47, v59, v38
	v_sub_f32_e32 v38, v126, v129
	v_mul_f32_e32 v48, v62, v39
	v_sub_f32_e32 v39, v127, v129
	v_mul_f32_e32 v38, 0x3fb8aa3b, v38
	v_mul_f32_e32 v39, 0x3fb8aa3b, v39
	v_exp_f32_e32 v38, v38
	v_exp_f32_e32 v39, v39
	v_cndmask_b32_e64 v43, v43, 0, s[78:79]
	v_lshlrev_b32_e32 v67, 16, v134
	v_cndmask_b32_e64 v38, v38, 0, s[86:87]
	v_cndmask_b32_e64 v39, v39, 0, s[84:85]
	v_mul_f32_e32 v40, v40, v38
	v_pk_mul_f32 v[44:45], v[44:45], v[38:39]
	v_mul_f32_e32 v38, v41, v39
	v_sub_f32_e32 v39, v60, v128
	v_mul_f32_e32 v39, 0x3fb8aa3b, v39
	v_exp_f32_e32 v39, v39
	v_cvt_pk_bf16_f32 v40, v40, s0
	v_cvt_pk_bf16_f32 v38, v38, s0
	ds_write_b16 v76, v40 offset:17472
	v_cndmask_b32_e64 v45, 0, v45, s[88:89]
	v_cndmask_b32_e64 v44, 0, v44, s[90:91]
	ds_write_b16 v69, v38 offset:17472
	ds_write_b128 v240, v[42:45] offset:8704
	v_cndmask_b32_e64 v38, v39, 0, s[92:93]
	v_mul_f32_e32 v30, v30, v38
	v_cvt_pk_bf16_f32 v30, v30, s0
	ds_write_b16 v111, v30 offset:17504
	v_sub_f32_e32 v30, v61, v128
	v_mul_f32_e32 v30, 0x3fb8aa3b, v30
	v_exp_f32_e32 v30, v30
	v_lshlrev_b32_e32 v46, 16, v123
	v_lshlrev_b32_e32 v49, 16, v136
	v_mul_f32_e32 v34, v34, v38
	v_cndmask_b32_e64 v30, v30, 0, s[96:97]
	v_mul_f32_e32 v35, v35, v30
	v_mul_f32_e32 v30, v31, v30
	v_cvt_pk_bf16_f32 v30, v30, s0
	ds_write_b16 v111, v30 offset:17648
	v_lshlrev_b32_e32 v30, 16, v125
	s_waitcnt lgkmcnt(14)
	v_lshlrev_b32_e32 v31, 16, v138
	v_fma_f32 v30, -v119, v51, v30
	v_fma_f32 v31, -v120, v52, v31
	v_mul_f32_e32 v39, v59, v30
	v_sub_f32_e32 v30, v126, v128
	v_mul_f32_e32 v40, v62, v31
	v_sub_f32_e32 v31, v127, v128
	v_mul_f32_e32 v30, 0x3fb8aa3b, v30
	v_mul_f32_e32 v31, 0x3fb8aa3b, v31
	v_exp_f32_e32 v30, v30
	v_exp_f32_e32 v31, v31
	v_lshlrev_b32_e32 v38, 16, v132
	v_lshlrev_b32_e32 v41, 16, v137
	v_cndmask_b32_e64 v30, v30, 0, s[0:1]
	v_cndmask_b32_e64 v31, v31, 0, s[98:99]
	v_mul_f32_e32 v32, v32, v30
	v_pk_mul_f32 v[36:37], v[36:37], v[30:31]
	v_mul_f32_e32 v30, v33, v31
	v_cvt_pk_bf16_f32 v32, v32, s0
	v_cvt_pk_bf16_f32 v30, v30, s0
	v_fma_f32 v64, -v118, v106, v64
	v_fma_f32 v67, -v121, v109, v67
	v_fma_f32 v46, -v118, v114, v46
	v_fma_f32 v49, -v121, v117, v49
	v_cndmask_b32_e64 v34, 0, v34, s[48:49]
	v_fma_f32 v38, -v118, v50, v38
	v_cndmask_b32_e64 v35, v35, 0, s[92:93]
	v_fma_f32 v41, -v121, v53, v41
	ds_write_b16 v76, v32 offset:17504
	v_cndmask_b32_e64 v37, 0, v37, s[2:3]
	v_cndmask_b32_e64 v36, 0, v36, s[4:5]
	ds_write_b16 v69, v30 offset:17504
	ds_write_b128 v240, v[34:37] offset:13056
	v_mul_f32_e32 v70, v62, v70
	v_mul_f32_e32 v68, v63, v71
	v_mul_f32_e32 v64, v58, v64
	v_mul_f32_e32 v67, v63, v67
	v_mul_f32_e32 v46, v58, v46
	v_mul_f32_e32 v49, v63, v49
	v_mul_f32_e32 v38, v58, v38
	v_mul_f32_e32 v41, v63, v41
	s_waitcnt lgkmcnt(0)
	s_barrier
; __device__ void dn_item(const Params& p, int l, int item, char* smem, int wv) {
;     ...
; #pragma unroll
;     for (int n = 0; n < 4; ++n)
; #pragma unroll
;       for (int j = 0; j < 4; ++j) X[(16 * wave + fq * 4 + j) * XS + n * 16 + fr] = rhs[n][j];
;     {
;       const int c = lane & 15;
;       const float* ld = LfT + (16 * wave) * 68 + 16 * wave;
;       float x[16];
; #pragma unroll
;       for (int i = 0; i < 16; ++i) x[i] = (i == c) ? 1.f : 0.f;
; #pragma unroll
;       for (int hb = 0; hb < 2; ++hb) {
;         const int j0 = hb ? 7 : 0, j1 = hb ? 15 : 7;
;         float4 lr[8][4];
; #pragma unroll
;         for (int jq = 0; jq < 8; ++jq) {
;           const int j = j0 + jq;
;           if (j < j1) {
; #pragma unroll
;             for (int q4 = 0; q4 < 4; ++q4)
;               if (q4 * 4 + 3 > j) lr[jq][q4] = *(const float4*)(ld + j * 68 + q4 * 4);
;           }
;         }
;         __builtin_amdgcn_sched_barrier(0);
; #pragma unroll
;         for (int jq = 0; jq < 8; ++jq) {
;           const int j = j0 + jq;
;           if (j < j1) {
;             const float xj = x[j];
; #pragma unroll
;             for (int q4 = 0; q4 < 4; ++q4) {
;               if (q4 * 4 + 3 > j) {
;                 float4 lq = lr[jq][q4];
;                 if (q4 * 4 + 0 > j) x[q4 * 4 + 0] -= lq.x * xj;
;                 if (q4 * 4 + 1 > j) x[q4 * 4 + 1] -= lq.y * xj;
;                 if (q4 * 4 + 2 > j) x[q4 * 4 + 2] -= lq.z * xj;
;                 if (q4 * 4 + 3 > j) x[q4 * 4 + 3] -= lq.w * xj;
;               }
;             }
;           }
;         }
;         __builtin_amdgcn_sched_barrier(0);
;       }
	ds_write_b32 v241, v133 offset:27200
	ds_write_b32 v241, v73 offset:27472
	ds_write_b32 v242, v70 offset:27200
	ds_write_b32 v243, v68 offset:27200
	ds_write_b32 v241, v64 offset:27264
	ds_write_b32 v241, v65 offset:27536
	ds_write_b32 v242, v66 offset:27264
	ds_write_b32 v243, v67 offset:27264
	ds_write_b32 v241, v46 offset:27328
	ds_write_b32 v241, v47 offset:27600
	ds_write_b32 v242, v48 offset:27328
	ds_write_b32 v243, v49 offset:27328
	ds_write_b32 v241, v38 offset:27392
	ds_write_b32 v241, v39 offset:27664
	ds_write_b32 v242, v40 offset:27392
	ds_write_b32 v243, v41 offset:27392
	ds_read_b32 v180, v191 offset:4
	ds_read_b64 v[30:31], v191 offset:8
	ds_read_b128 v[32:35], v191 offset:16
	ds_read_b128 v[36:39], v191 offset:32
	ds_read_b128 v[40:43], v191 offset:48
	ds_read_b64 v[44:45], v191 offset:280
	ds_read_b128 v[46:49], v191 offset:288
	ds_read_b128 v[50:53], v191 offset:304
	ds_read_b128 v[54:57], v191 offset:320
	ds_read_b32 v179, v191 offset:556
	ds_read_b128 v[58:61], v191 offset:560
	ds_read_b128 v[62:65], v191 offset:576
	ds_read_b128 v[66:69], v191 offset:592
	ds_read_b128 v[70:73], v191 offset:832
	ds_read_b128 v[74:77], v191 offset:848
	ds_read_b128 v[106:109], v191 offset:864
	ds_read_b32 v176, v191 offset:1108
	ds_read_b64 v[110:111], v191 offset:1112
	ds_read_b128 v[112:115], v191 offset:1120
	ds_read_b128 v[116:119], v191 offset:1136
	ds_read_b64 v[120:121], v191 offset:1384
	ds_read_b128 v[122:125], v191 offset:1392
	ds_read_b128 v[126:129], v191 offset:1408
	ds_read_b32 v132, v191 offset:1660
	ds_read_b128 v[134:137], v191 offset:1664
	ds_read_b128 v[138:141], v191 offset:1680
	s_and_saveexec_b64 s[6:7], s[46:47]
	s_cbranch_execz .LBB0_359
	s_waitcnt lgkmcnt(13)
	v_fma_f32 v161, -v180, v218, v219
	v_pk_fma_f32 v[162:163], v[30:31], v[218:219], v[220:221] op_sel_hi:[1,0,1] neg_lo:[1,0,0] neg_hi:[1,0,0]
	v_pk_fma_f32 v[164:165], v[32:33], v[218:219], v[222:223] op_sel_hi:[1,0,1] neg_lo:[1,0,0] neg_hi:[1,0,0]
	v_pk_fma_f32 v[166:167], v[34:35], v[218:219], v[224:225] op_sel_hi:[1,0,1] neg_lo:[1,0,0] neg_hi:[1,0,0]
	v_pk_fma_f32 v[168:169], v[36:37], v[218:219], v[226:227] op_sel_hi:[1,0,1] neg_lo:[1,0,0] neg_hi:[1,0,0]
	v_pk_fma_f32 v[170:171], v[38:39], v[218:219], v[228:229] op_sel_hi:[1,0,1] neg_lo:[1,0,0] neg_hi:[1,0,0]
	v_pk_fma_f32 v[172:173], v[40:41], v[218:219], v[230:231] op_sel_hi:[1,0,1] neg_lo:[1,0,0] neg_hi:[1,0,0]
	v_pk_fma_f32 v[174:175], v[42:43], v[218:219], v[232:233] op_sel_hi:[1,0,1] neg_lo:[1,0,0] neg_hi:[1,0,0]
	v_pk_fma_f32 v[162:163], v[44:45], v[160:161], v[162:163] op_sel:[0,1,0] op_sel_hi:[1,1,1] neg_lo:[1,0,0] neg_hi:[1,0,0]
	v_pk_fma_f32 v[164:165], v[46:47], v[160:161], v[164:165] op_sel:[0,1,0] op_sel_hi:[1,1,1] neg_lo:[1,0,0] neg_hi:[1,0,0]
	v_pk_fma_f32 v[166:167], v[48:49], v[160:161], v[166:167] op_sel:[0,1,0] op_sel_hi:[1,1,1] neg_lo:[1,0,0] neg_hi:[1,0,0]
	v_pk_fma_f32 v[168:169], v[50:51], v[160:161], v[168:169] op_sel:[0,1,0] op_sel_hi:[1,1,1] neg_lo:[1,0,0] neg_hi:[1,0,0]
	v_pk_fma_f32 v[170:171], v[52:53], v[160:161], v[170:171] op_sel:[0,1,0] op_sel_hi:[1,1,1] neg_lo:[1,0,0] neg_hi:[1,0,0]
	v_pk_fma_f32 v[172:173], v[54:55], v[160:161], v[172:173] op_sel:[0,1,0] op_sel_hi:[1,1,1] neg_lo:[1,0,0] neg_hi:[1,0,0]
	v_pk_fma_f32 v[174:175], v[56:57], v[160:161], v[174:175] op_sel:[0,1,0] op_sel_hi:[1,1,1] neg_lo:[1,0,0] neg_hi:[1,0,0]
	v_fma_f32 v163, -v179, v162, v163
	v_pk_fma_f32 v[164:165], v[58:59], v[162:163], v[164:165] op_sel_hi:[1,0,1] neg_lo:[1,0,0] neg_hi:[1,0,0]
	v_pk_fma_f32 v[166:167], v[60:61], v[162:163], v[166:167] op_sel_hi:[1,0,1] neg_lo:[1,0,0] neg_hi:[1,0,0]
	v_pk_fma_f32 v[168:169], v[62:63], v[162:163], v[168:169] op_sel_hi:[1,0,1] neg_lo:[1,0,0] neg_hi:[1,0,0]
	v_pk_fma_f32 v[170:171], v[64:65], v[162:163], v[170:171] op_sel_hi:[1,0,1] neg_lo:[1,0,0] neg_hi:[1,0,0]
	v_pk_fma_f32 v[172:173], v[66:67], v[162:163], v[172:173] op_sel_hi:[1,0,1] neg_lo:[1,0,0] neg_hi:[1,0,0]
	v_pk_fma_f32 v[174:175], v[68:69], v[162:163], v[174:175] op_sel_hi:[1,0,1] neg_lo:[1,0,0] neg_hi:[1,0,0]
	ds_read_b128 v[54:57], v191 offset:1936
	ds_read_b128 v[50:53], v191 offset:1952
	ds_read_b32 v180, v191 offset:2212
	ds_read_b64 v[44:45], v191 offset:2216
	ds_read_b128 v[46:49], v191 offset:2224
	ds_read_b64 v[30:31], v191 offset:2488
	ds_read_b128 v[40:43], v191 offset:2496
	ds_read_b32 v133, v191 offset:2764
	ds_read_b128 v[36:39], v191 offset:2768
	ds_read_b128 v[32:35], v191 offset:3040
	ds_read_b32 v142, v191 offset:3316
	ds_read_b64 v[144:145], v191 offset:3320
	ds_read_b64 v[146:147], v191 offset:3592
	ds_read_b32 v143, v191 offset:3868
	s_waitcnt lgkmcnt(14)
; __device__ void dn_item(const Params& p, int l, int item, char* smem, int wv) {
;     ...
; #pragma unroll
;         for (int jq = 0; jq < 8; ++jq) {
;           const int j = j0 + jq;
;           if (j < j1) {
;             const float xj = x[j];
; #pragma unroll
;             for (int q4 = 0; q4 < 4; ++q4) {
;               if (q4 * 4 + 3 > j) {
;                 float4 lq = lr[jq][q4];
;                 if (q4 * 4 + 0 > j) x[q4 * 4 + 0] -= lq.x * xj;
;                 if (q4 * 4 + 1 > j) x[q4 * 4 + 1] -= lq.y * xj;
;                 if (q4 * 4 + 2 > j) x[q4 * 4 + 2] -= lq.z * xj;
;                 if (q4 * 4 + 3 > j) x[q4 * 4 + 3] -= lq.w * xj;
;               }
;             }
;           }
;         }
;         __builtin_amdgcn_sched_barrier(0);
;       }
;       if (lane < 16) {
; #pragma unroll
;         for (int i = 0; i < 16; ++i) Tinv[(wave * 16 + i) * 16 + c] = x[i];
;       }
	v_pk_fma_f32 v[164:165], v[70:71], v[162:163], v[164:165] op_sel:[0,1,0] op_sel_hi:[1,1,1] neg_lo:[1,0,0] neg_hi:[1,0,0]
	v_pk_fma_f32 v[166:167], v[72:73], v[162:163], v[166:167] op_sel:[0,1,0] op_sel_hi:[1,1,1] neg_lo:[1,0,0] neg_hi:[1,0,0]
	v_pk_fma_f32 v[168:169], v[74:75], v[162:163], v[168:169] op_sel:[0,1,0] op_sel_hi:[1,1,1] neg_lo:[1,0,0] neg_hi:[1,0,0]
	v_pk_fma_f32 v[170:171], v[76:77], v[162:163], v[170:171] op_sel:[0,1,0] op_sel_hi:[1,1,1] neg_lo:[1,0,0] neg_hi:[1,0,0]
	v_pk_fma_f32 v[172:173], v[106:107], v[162:163], v[172:173] op_sel:[0,1,0] op_sel_hi:[1,1,1] neg_lo:[1,0,0] neg_hi:[1,0,0]
	v_pk_fma_f32 v[174:175], v[108:109], v[162:163], v[174:175] op_sel:[0,1,0] op_sel_hi:[1,1,1] neg_lo:[1,0,0] neg_hi:[1,0,0]
	v_fma_f32 v165, -v176, v164, v165
	v_pk_fma_f32 v[166:167], v[110:111], v[164:165], v[166:167] op_sel_hi:[1,0,1] neg_lo:[1,0,0] neg_hi:[1,0,0]
	v_pk_fma_f32 v[168:169], v[112:113], v[164:165], v[168:169] op_sel_hi:[1,0,1] neg_lo:[1,0,0] neg_hi:[1,0,0]
	v_pk_fma_f32 v[170:171], v[114:115], v[164:165], v[170:171] op_sel_hi:[1,0,1] neg_lo:[1,0,0] neg_hi:[1,0,0]
	v_pk_fma_f32 v[172:173], v[116:117], v[164:165], v[172:173] op_sel_hi:[1,0,1] neg_lo:[1,0,0] neg_hi:[1,0,0]
	v_pk_fma_f32 v[174:175], v[118:119], v[164:165], v[174:175] op_sel_hi:[1,0,1] neg_lo:[1,0,0] neg_hi:[1,0,0]
	v_pk_fma_f32 v[166:167], v[120:121], v[164:165], v[166:167] op_sel:[0,1,0] op_sel_hi:[1,1,1] neg_lo:[1,0,0] neg_hi:[1,0,0]
	v_pk_fma_f32 v[168:169], v[122:123], v[164:165], v[168:169] op_sel:[0,1,0] op_sel_hi:[1,1,1] neg_lo:[1,0,0] neg_hi:[1,0,0]
	v_pk_fma_f32 v[170:171], v[124:125], v[164:165], v[170:171] op_sel:[0,1,0] op_sel_hi:[1,1,1] neg_lo:[1,0,0] neg_hi:[1,0,0]
	v_pk_fma_f32 v[172:173], v[126:127], v[164:165], v[172:173] op_sel:[0,1,0] op_sel_hi:[1,1,1] neg_lo:[1,0,0] neg_hi:[1,0,0]
	v_pk_fma_f32 v[174:175], v[128:129], v[164:165], v[174:175] op_sel:[0,1,0] op_sel_hi:[1,1,1] neg_lo:[1,0,0] neg_hi:[1,0,0]
	v_fma_f32 v167, -v132, v166, v167
	v_pk_fma_f32 v[168:169], v[134:135], v[166:167], v[168:169] op_sel_hi:[1,0,1] neg_lo:[1,0,0] neg_hi:[1,0,0]
	v_pk_fma_f32 v[170:171], v[136:137], v[166:167], v[170:171] op_sel_hi:[1,0,1] neg_lo:[1,0,0] neg_hi:[1,0,0]
	v_pk_fma_f32 v[172:173], v[138:139], v[166:167], v[172:173] op_sel_hi:[1,0,1] neg_lo:[1,0,0] neg_hi:[1,0,0]
	v_pk_fma_f32 v[174:175], v[140:141], v[166:167], v[174:175] op_sel_hi:[1,0,1] neg_lo:[1,0,0] neg_hi:[1,0,0]
	s_waitcnt lgkmcnt(0)
	v_pk_fma_f32 v[168:169], v[54:55], v[166:167], v[168:169] op_sel:[0,1,0] op_sel_hi:[1,1,1] neg_lo:[1,0,0] neg_hi:[1,0,0]
	v_pk_fma_f32 v[170:171], v[56:57], v[166:167], v[170:171] op_sel:[0,1,0] op_sel_hi:[1,1,1] neg_lo:[1,0,0] neg_hi:[1,0,0]
	v_pk_fma_f32 v[172:173], v[50:51], v[166:167], v[172:173] op_sel:[0,1,0] op_sel_hi:[1,1,1] neg_lo:[1,0,0] neg_hi:[1,0,0]
	v_pk_fma_f32 v[174:175], v[52:53], v[166:167], v[174:175] op_sel:[0,1,0] op_sel_hi:[1,1,1] neg_lo:[1,0,0] neg_hi:[1,0,0]
	v_fma_f32 v169, -v180, v168, v169
	v_pk_fma_f32 v[170:171], v[44:45], v[168:169], v[170:171] op_sel_hi:[1,0,1] neg_lo:[1,0,0] neg_hi:[1,0,0]
	v_pk_fma_f32 v[172:173], v[46:47], v[168:169], v[172:173] op_sel_hi:[1,0,1] neg_lo:[1,0,0] neg_hi:[1,0,0]
	v_pk_fma_f32 v[174:175], v[48:49], v[168:169], v[174:175] op_sel_hi:[1,0,1] neg_lo:[1,0,0] neg_hi:[1,0,0]
	v_pk_fma_f32 v[170:171], v[30:31], v[168:169], v[170:171] op_sel:[0,1,0] op_sel_hi:[1,1,1] neg_lo:[1,0,0] neg_hi:[1,0,0]
	v_pk_fma_f32 v[172:173], v[40:41], v[168:169], v[172:173] op_sel:[0,1,0] op_sel_hi:[1,1,1] neg_lo:[1,0,0] neg_hi:[1,0,0]
	v_pk_fma_f32 v[174:175], v[42:43], v[168:169], v[174:175] op_sel:[0,1,0] op_sel_hi:[1,1,1] neg_lo:[1,0,0] neg_hi:[1,0,0]
	v_fma_f32 v171, -v133, v170, v171
	v_pk_fma_f32 v[172:173], v[36:37], v[170:171], v[172:173] op_sel_hi:[1,0,1] neg_lo:[1,0,0] neg_hi:[1,0,0]
	v_pk_fma_f32 v[174:175], v[38:39], v[170:171], v[174:175] op_sel_hi:[1,0,1] neg_lo:[1,0,0] neg_hi:[1,0,0]
	v_pk_fma_f32 v[172:173], v[32:33], v[170:171], v[172:173] op_sel:[0,1,0] op_sel_hi:[1,1,1] neg_lo:[1,0,0] neg_hi:[1,0,0]
	v_pk_fma_f32 v[174:175], v[34:35], v[170:171], v[174:175] op_sel:[0,1,0] op_sel_hi:[1,1,1] neg_lo:[1,0,0] neg_hi:[1,0,0]
	v_fma_f32 v173, -v142, v172, v173
	v_pk_fma_f32 v[174:175], v[144:145], v[172:173], v[174:175] op_sel_hi:[1,0,1] neg_lo:[1,0,0] neg_hi:[1,0,0]
	v_pk_fma_f32 v[174:175], v[146:147], v[172:173], v[174:175] op_sel:[0,1,0] op_sel_hi:[1,1,1] neg_lo:[1,0,0] neg_hi:[1,0,0]
	v_fma_f32 v175, -v143, v174, v175
	ds_write2_b32 v192, v218, v161 offset1:16
	ds_write2_b32 v192, v162, v163 offset0:32 offset1:48
	ds_write2_b32 v192, v164, v165 offset0:64 offset1:80
	ds_write2_b32 v192, v166, v167 offset0:96 offset1:112
	ds_write2_b32 v192, v168, v169 offset0:128 offset1:144
	ds_write2_b32 v192, v170, v171 offset0:160 offset1:176
	ds_write2_b32 v192, v172, v173 offset0:192 offset1:208
	ds_write2_b32 v192, v174, v175 offset0:224 offset1:240
